# v20 + acc-major MFMA order: the two K-half MFMAs of each accumulator issued back to back (SrcC forwarding)
# speedup vs baseline: 1.0031x; 1.0014x over previous
; #define PG8_STAGE(bufoff, gbase, voff) do { _Pragma("unroll") for (int _i = 0; _i < 2; ++_i) \
;         __builtin_amdgcn_global_load_lds((const unsigned*)((const char*)(gbase) + (voff)[_i]), (PG8_LAS unsigned*)(lds + (bufoff) + ldsw + _i * 8192), 16, 0, 0); } while (0)
; #define PG8_WAIT_V(n) asm volatile("s_waitcnt vmcnt(" #n ")" ::: "memory")
; #define PG8_WAIT_L(n) asm volatile("s_waitcnt lgkmcnt(" #n ")" ::: "memory")
; #define PG8_BAR __builtin_amdgcn_s_barrier()
; #define PG8_SCHED __builtin_amdgcn_sched_barrier(0)
;     ...
;             PG8_LDB(B0, 0, 0); PG8_LDB(B1, 0, 1); PG8_SCHED; PG8_LDA(At, 0, 0); PG8_STAGE(PG8_SA(1, 1), a1 + hstep, voffA);
;             PG8_WAIT_V(8); PG8_WAIT_L(0); PG8_BAR; PG8_MMA(0, 0, At, B0); PG8_MMA(0, 1, At, B1); PG8_BAR; PG8_SCHED;
.LBB0_248:
	v_add_u32_e32 v155, s68, v149
	ds_read_b128 v[166:169], v155
	ds_read_b128 v[170:173], v155 offset:1024
	ds_read_b128 v[174:177], v155 offset:2048
	ds_read_b128 v[178:181], v155 offset:3072
	v_add_u32_e32 v155, s69, v149
	ds_read_b128 v[182:185], v155
	ds_read_b128 v[186:189], v155 offset:1024
	ds_read_b128 v[190:193], v155 offset:2048
	ds_read_b128 v[194:197], v155 offset:3072
	s_add_u32 s33, s50, 0xfffc0080
	s_addc_u32 s54, s51, -1
	s_and_b64 s[52:53], s[52:53], exec
	s_cselect_b32 s55, s25, s54
	s_cselect_b32 s54, s34, s33
	s_cselect_b32 s53, s21, s73
	s_cselect_b32 s52, s35, s72
	v_lshl_add_u64 v[210:211], s[50:51], 0, v[138:139]
	s_add_i32 m0, s59, 0xc000
	ds_read_b128 v[198:201], v153
	ds_read_b128 v[202:205], v153 offset:1024
	ds_read_b128 v[206:209], v153 offset:2048
	ds_read_b128 v[214:217], v153 offset:3072
	ds_read_b128 v[218:221], v153 offset:4096
	ds_read_b128 v[222:225], v153 offset:5120
	ds_read_b128 v[226:229], v153 offset:6144
	ds_read_b128 v[230:233], v153 offset:7168
	global_load_lds_dwordx4 v[210:211], off
	v_lshl_add_u64 v[210:211], s[50:51], 0, v[140:141]
	s_add_i32 m0, s59, 0xe000
	s_nop 0
	global_load_lds_dwordx4 v[210:211], off
	s_waitcnt vmcnt(8)
	s_waitcnt lgkmcnt(0)
	s_barrier
	s_setprio 1
	s_waitcnt lgkmcnt(0)
	v_mfma_i32_16x16x64_i8 v[124:127], v[166:169], v[198:201], v[124:127]
	v_mfma_i32_16x16x64_i8 v[124:127], v[170:173], v[202:205], v[124:127]
	v_mfma_i32_16x16x64_i8 v[116:119], v[174:177], v[198:201], v[116:119]
	v_mfma_i32_16x16x64_i8 v[116:119], v[178:181], v[202:205], v[116:119]
	v_mfma_i32_16x16x64_i8 v[108:111], v[166:169], v[206:209], v[108:111]
	v_mfma_i32_16x16x64_i8 v[108:111], v[170:173], v[214:217], v[108:111]
	v_mfma_i32_16x16x64_i8 v[100:103], v[174:177], v[206:209], v[100:103]
	v_mfma_i32_16x16x64_i8 v[100:103], v[178:181], v[214:217], v[100:103]
	v_mfma_i32_16x16x64_i8 v[92:95], v[166:169], v[218:221], v[92:95]
	v_mfma_i32_16x16x64_i8 v[92:95], v[170:173], v[222:225], v[92:95]
	v_mfma_i32_16x16x64_i8 v[84:87], v[174:177], v[218:221], v[84:87]
	v_mfma_i32_16x16x64_i8 v[84:87], v[178:181], v[222:225], v[84:87]
	v_mfma_i32_16x16x64_i8 v[76:79], v[166:169], v[226:229], v[76:79]
	v_mfma_i32_16x16x64_i8 v[76:79], v[170:173], v[230:233], v[76:79]
	v_mfma_i32_16x16x64_i8 v[68:71], v[174:177], v[226:229], v[68:71]
	v_mfma_i32_16x16x64_i8 v[68:71], v[178:181], v[230:233], v[68:71]
	s_setprio 0
	s_setprio 1
	v_mfma_i32_16x16x64_i8 v[120:123], v[182:185], v[198:201], v[120:123]
	v_mfma_i32_16x16x64_i8 v[120:123], v[186:189], v[202:205], v[120:123]
	v_mfma_i32_16x16x64_i8 v[112:115], v[190:193], v[198:201], v[112:115]
	v_mfma_i32_16x16x64_i8 v[112:115], v[194:197], v[202:205], v[112:115]
	v_mfma_i32_16x16x64_i8 v[104:107], v[182:185], v[206:209], v[104:107]
	v_mfma_i32_16x16x64_i8 v[104:107], v[186:189], v[214:217], v[104:107]
	v_mfma_i32_16x16x64_i8 v[96:99], v[190:193], v[206:209], v[96:99]
	v_mfma_i32_16x16x64_i8 v[96:99], v[194:197], v[214:217], v[96:99]
	v_mfma_i32_16x16x64_i8 v[88:91], v[182:185], v[218:221], v[88:91]
	v_mfma_i32_16x16x64_i8 v[88:91], v[186:189], v[222:225], v[88:91]
	v_mfma_i32_16x16x64_i8 v[80:83], v[190:193], v[218:221], v[80:83]
	v_mfma_i32_16x16x64_i8 v[80:83], v[194:197], v[222:225], v[80:83]
	v_mfma_i32_16x16x64_i8 v[72:75], v[182:185], v[226:229], v[72:75]
	v_mfma_i32_16x16x64_i8 v[72:75], v[186:189], v[230:233], v[72:75]
	v_mfma_i32_16x16x64_i8 v[64:67], v[190:193], v[226:229], v[64:67]
	v_mfma_i32_16x16x64_i8 v[64:67], v[194:197], v[230:233], v[64:67]
	s_setprio 0
	s_barrier
	s_add_i32 s33, s68, s56
	v_lshl_add_u64 v[210:211], s[52:53], 0, v[132:133]
	s_mov_b32 m0, s33
	ds_read_b128 v[198:201], v153 offset:16384
	ds_read_b128 v[202:205], v153 offset:17408
	ds_read_b128 v[206:209], v153 offset:18432
	ds_read_b128 v[214:217], v153 offset:19456
	ds_read_b128 v[218:221], v153 offset:20480
	ds_read_b128 v[222:225], v153 offset:21504
	ds_read_b128 v[226:229], v153 offset:22528
	ds_read_b128 v[230:233], v153 offset:23552
	global_load_lds_dwordx4 v[210:211], off
	s_add_i32 m0, s33, 0x2000
	s_add_u32 s76, s52, 0x40000
	v_lshl_add_u64 v[234:235], s[52:53], 0, v[128:129]
	s_addc_u32 s77, s53, 0
	s_add_i32 s33, s69, s56
	global_load_lds_dwordx4 v[234:235], off
	v_lshl_add_u64 v[236:237], s[76:77], 0, v[132:133]
	s_mov_b32 m0, s33
	v_lshl_add_u64 v[238:239], s[54:55], 0, v[130:131]
	global_load_lds_dwordx4 v[236:237], off
	v_lshl_add_u64 v[236:237], s[76:77], 0, v[128:129]
	s_add_i32 m0, s33, 0x2000
	s_nop 0
	global_load_lds_dwordx4 v[236:237], off
	v_lshl_add_u64 v[236:237], s[54:55], 0, v[134:135]
	s_mov_b32 m0, s59
	s_nop 0
	global_load_lds_dwordx4 v[236:237], off
	s_mov_b32 m0, s60
	s_nop 0
	global_load_lds_dwordx4 v[238:239], off
	s_waitcnt vmcnt(8)
	s_waitcnt lgkmcnt(0)
	s_barrier
; #define PG8_STAGE(bufoff, gbase, voff) do { _Pragma("unroll") for (int _i = 0; _i < 2; ++_i) \
;         __builtin_amdgcn_global_load_lds((const unsigned*)((const char*)(gbase) + (voff)[_i]), (PG8_LAS unsigned*)(lds + (bufoff) + ldsw + _i * 8192), 16, 0, 0); } while (0)
; #define PG8_WAIT_V(n) asm volatile("s_waitcnt vmcnt(" #n ")" ::: "memory")
; #define PG8_WAIT_L(n) asm volatile("s_waitcnt lgkmcnt(" #n ")" ::: "memory")
; #define PG8_BAR __builtin_amdgcn_s_barrier()
; #define PG8_SCHED __builtin_amdgcn_sched_barrier(0)
;     ...
;             PG8_WAIT_V(8); PG8_WAIT_L(0); PG8_BAR; PG8_MMA(0, 0, At, B0); PG8_MMA(0, 1, At, B1); PG8_BAR; PG8_SCHED;
;             PG8_LDA(At, 0, 1); PG8_STAGE(PG8_SB(0, 0), b2, voffB); PG8_STAGE(PG8_SB(0, 1), b2 + hstep, voffB); PG8_STAGE(PG8_SA(0, 0), a2, voffA);
;             PG8_WAIT_V(8); PG8_WAIT_L(0); PG8_BAR; PG8_MMA(1, 0, At, B0); PG8_MMA(1, 1, At, B1); PG8_BAR; PG8_SCHED;
;             PG8_LDB(B0, 1, 0); PG8_LDB(B1, 1, 1); PG8_SCHED; PG8_LDA(At, 1, 0); PG8_STAGE(PG8_SA(0, 1), a2 + hstep, voffA);
;             PG8_WAIT_V(8); PG8_WAIT_L(0); PG8_BAR; PG8_MMA(0, 0, At, B0); PG8_MMA(0, 1, At, B1); PG8_BAR; PG8_SCHED;
;             PG8_LDA(At, 1, 1); PG8_STAGE(PG8_SB(1, 0), b3, voffB); PG8_STAGE(PG8_SB(1, 1), b3 + hstep, voffB); PG8_STAGE(PG8_SA(1, 0), a3, voffA);
;             PG8_WAIT_V(8); PG8_WAIT_L(0); PG8_BAR; PG8_MMA(1, 0, At, B0); PG8_MMA(1, 1, At, B1); PG8_BAR; PG8_SCHED;
	s_setprio 1
	s_waitcnt lgkmcnt(0)
	v_mfma_i32_16x16x64_i8 v[60:63], v[166:169], v[198:201], v[60:63]
	v_mfma_i32_16x16x64_i8 v[60:63], v[170:173], v[202:205], v[60:63]
	v_mfma_i32_16x16x64_i8 v[52:55], v[174:177], v[198:201], v[52:55]
	v_mfma_i32_16x16x64_i8 v[52:55], v[178:181], v[202:205], v[52:55]
	v_mfma_i32_16x16x64_i8 v[44:47], v[166:169], v[206:209], v[44:47]
	v_mfma_i32_16x16x64_i8 v[44:47], v[170:173], v[214:217], v[44:47]
	v_mfma_i32_16x16x64_i8 v[36:39], v[174:177], v[206:209], v[36:39]
	v_mfma_i32_16x16x64_i8 v[36:39], v[178:181], v[214:217], v[36:39]
	v_mfma_i32_16x16x64_i8 v[28:31], v[166:169], v[218:221], v[28:31]
	v_mfma_i32_16x16x64_i8 v[28:31], v[170:173], v[222:225], v[28:31]
	v_mfma_i32_16x16x64_i8 v[20:23], v[174:177], v[218:221], v[20:23]
	v_mfma_i32_16x16x64_i8 v[20:23], v[178:181], v[222:225], v[20:23]
	v_mfma_i32_16x16x64_i8 v[12:15], v[166:169], v[226:229], v[12:15]
	v_mfma_i32_16x16x64_i8 v[12:15], v[170:173], v[230:233], v[12:15]
	v_mfma_i32_16x16x64_i8 v[4:7], v[174:177], v[226:229], v[4:7]
	v_mfma_i32_16x16x64_i8 v[4:7], v[178:181], v[230:233], v[4:7]
	s_setprio 0
	s_setprio 1
	v_mfma_i32_16x16x64_i8 v[56:59], v[182:185], v[198:201], v[56:59]
	v_mfma_i32_16x16x64_i8 v[56:59], v[186:189], v[202:205], v[56:59]
	v_mfma_i32_16x16x64_i8 v[48:51], v[190:193], v[198:201], v[48:51]
	v_mfma_i32_16x16x64_i8 v[48:51], v[194:197], v[202:205], v[48:51]
	v_mfma_i32_16x16x64_i8 v[40:43], v[182:185], v[206:209], v[40:43]
	v_mfma_i32_16x16x64_i8 v[40:43], v[186:189], v[214:217], v[40:43]
	v_mfma_i32_16x16x64_i8 v[32:35], v[190:193], v[206:209], v[32:35]
	v_mfma_i32_16x16x64_i8 v[32:35], v[194:197], v[214:217], v[32:35]
	v_mfma_i32_16x16x64_i8 v[24:27], v[182:185], v[218:221], v[24:27]
	v_mfma_i32_16x16x64_i8 v[24:27], v[186:189], v[222:225], v[24:27]
	v_mfma_i32_16x16x64_i8 v[16:19], v[190:193], v[218:221], v[16:19]
	v_mfma_i32_16x16x64_i8 v[16:19], v[194:197], v[222:225], v[16:19]
	v_mfma_i32_16x16x64_i8 v[8:11], v[182:185], v[226:229], v[8:11]
	v_mfma_i32_16x16x64_i8 v[8:11], v[186:189], v[230:233], v[8:11]
	v_mfma_i32_16x16x64_i8 v[0:3], v[190:193], v[226:229], v[0:3]
	v_mfma_i32_16x16x64_i8 v[0:3], v[194:197], v[230:233], v[0:3]
	s_setprio 0
	s_barrier
	s_add_i32 s33, 0, 0x18000
	v_add_u32_e32 v155, s33, v149
	s_add_i32 s75, 0, 0x1c000
	ds_read_b128 v[166:169], v155
	ds_read_b128 v[170:173], v155 offset:1024
	ds_read_b128 v[174:177], v155 offset:2048
	ds_read_b128 v[178:181], v155 offset:3072
	v_add_u32_e32 v155, s75, v149
	ds_read_b128 v[182:185], v155
	ds_read_b128 v[186:189], v155 offset:1024
	ds_read_b128 v[190:193], v155 offset:2048
	ds_read_b128 v[194:197], v155 offset:3072
	s_add_u32 s54, s54, 0x40000
	s_addc_u32 s55, s55, 0
	s_mov_b32 m0, s61
	v_lshl_add_u64 v[240:241], s[54:55], 0, v[134:135]
	ds_read_b128 v[198:201], v153 offset:32768
	ds_read_b128 v[202:205], v153 offset:33792
	ds_read_b128 v[206:209], v153 offset:34816
	ds_read_b128 v[214:217], v153 offset:35840
	ds_read_b128 v[218:221], v153 offset:36864
	ds_read_b128 v[222:225], v153 offset:37888
	ds_read_b128 v[226:229], v153 offset:38912
	ds_read_b128 v[230:233], v153 offset:39936
	global_load_lds_dwordx4 v[240:241], off
	v_lshl_add_u64 v[240:241], s[54:55], 0, v[130:131]
	s_mov_b32 m0, s62
	s_nop 0
	global_load_lds_dwordx4 v[240:241], off
	s_waitcnt vmcnt(8)
	s_waitcnt lgkmcnt(0)
	s_barrier
	s_setprio 1
	s_waitcnt lgkmcnt(0)
	v_mfma_i32_16x16x64_i8 v[124:127], v[166:169], v[198:201], v[124:127]
	v_mfma_i32_16x16x64_i8 v[124:127], v[170:173], v[202:205], v[124:127]
	v_mfma_i32_16x16x64_i8 v[116:119], v[174:177], v[198:201], v[116:119]
	v_mfma_i32_16x16x64_i8 v[116:119], v[178:181], v[202:205], v[116:119]
	v_mfma_i32_16x16x64_i8 v[108:111], v[166:169], v[206:209], v[108:111]
	v_mfma_i32_16x16x64_i8 v[108:111], v[170:173], v[214:217], v[108:111]
	v_mfma_i32_16x16x64_i8 v[100:103], v[174:177], v[206:209], v[100:103]
	v_mfma_i32_16x16x64_i8 v[100:103], v[178:181], v[214:217], v[100:103]
	v_mfma_i32_16x16x64_i8 v[92:95], v[166:169], v[218:221], v[92:95]
	v_mfma_i32_16x16x64_i8 v[92:95], v[170:173], v[222:225], v[92:95]
	v_mfma_i32_16x16x64_i8 v[84:87], v[174:177], v[218:221], v[84:87]
	v_mfma_i32_16x16x64_i8 v[84:87], v[178:181], v[222:225], v[84:87]
	v_mfma_i32_16x16x64_i8 v[76:79], v[166:169], v[226:229], v[76:79]
	v_mfma_i32_16x16x64_i8 v[76:79], v[170:173], v[230:233], v[76:79]
	v_mfma_i32_16x16x64_i8 v[68:71], v[174:177], v[226:229], v[68:71]
	v_mfma_i32_16x16x64_i8 v[68:71], v[178:181], v[230:233], v[68:71]
	s_setprio 0
	s_setprio 1
	v_mfma_i32_16x16x64_i8 v[120:123], v[182:185], v[198:201], v[120:123]
	v_mfma_i32_16x16x64_i8 v[120:123], v[186:189], v[202:205], v[120:123]
	v_mfma_i32_16x16x64_i8 v[112:115], v[190:193], v[198:201], v[112:115]
	v_mfma_i32_16x16x64_i8 v[112:115], v[194:197], v[202:205], v[112:115]
	v_mfma_i32_16x16x64_i8 v[104:107], v[182:185], v[206:209], v[104:107]
	v_mfma_i32_16x16x64_i8 v[104:107], v[186:189], v[214:217], v[104:107]
	v_mfma_i32_16x16x64_i8 v[96:99], v[190:193], v[206:209], v[96:99]
	v_mfma_i32_16x16x64_i8 v[96:99], v[194:197], v[214:217], v[96:99]
	v_mfma_i32_16x16x64_i8 v[88:91], v[182:185], v[218:221], v[88:91]
	v_mfma_i32_16x16x64_i8 v[88:91], v[186:189], v[222:225], v[88:91]
	v_mfma_i32_16x16x64_i8 v[80:83], v[190:193], v[218:221], v[80:83]
	v_mfma_i32_16x16x64_i8 v[80:83], v[194:197], v[222:225], v[80:83]
	v_mfma_i32_16x16x64_i8 v[72:75], v[182:185], v[226:229], v[72:75]
	v_mfma_i32_16x16x64_i8 v[72:75], v[186:189], v[230:233], v[72:75]
	v_mfma_i32_16x16x64_i8 v[64:67], v[190:193], v[226:229], v[64:67]
	v_mfma_i32_16x16x64_i8 v[64:67], v[194:197], v[230:233], v[64:67]
	s_setprio 0
	s_barrier
	s_add_i32 s33, s33, s56
	v_lshl_add_u64 v[210:211], v[210:211], 0, s[10:11]
	s_mov_b32 m0, s33
	ds_read_b128 v[198:201], v153 offset:49152
	ds_read_b128 v[202:205], v153 offset:50176
	ds_read_b128 v[206:209], v153 offset:51200
	ds_read_b128 v[214:217], v153 offset:52224
	ds_read_b128 v[218:221], v153 offset:53248
	ds_read_b128 v[222:225], v153 offset:54272
	ds_read_b128 v[226:229], v153 offset:55296
	ds_read_b128 v[230:233], v153 offset:56320
	global_load_lds_dwordx4 v[210:211], off
	s_add_i32 m0, s33, 0x2000
	s_add_u32 s52, s52, 0x40080
	v_lshl_add_u64 v[210:211], v[234:235], 0, s[10:11]
	s_addc_u32 s53, s53, 0
	s_add_i32 s33, s75, s56
	global_load_lds_dwordx4 v[210:211], off
	v_lshl_add_u64 v[210:211], s[52:53], 0, v[132:133]
	s_mov_b32 m0, s33
	s_nop 0
	global_load_lds_dwordx4 v[210:211], off
	v_lshl_add_u64 v[210:211], s[52:53], 0, v[128:129]
	s_add_i32 m0, s33, 0x2000
	s_nop 0
	global_load_lds_dwordx4 v[210:211], off
	v_lshl_add_u64 v[210:211], v[236:237], 0, s[10:11]
	s_mov_b32 m0, s64
	s_nop 0
	global_load_lds_dwordx4 v[210:211], off
	v_lshl_add_u64 v[210:211], v[238:239], 0, s[10:11]
	s_mov_b32 m0, s65
	s_nop 0
	global_load_lds_dwordx4 v[210:211], off
	s_waitcnt vmcnt(8)
	s_waitcnt lgkmcnt(0)
	s_barrier
	s_cmp_eq_u32 s74, 12
	s_cbranch_scc1 .Lp1_cm_load
; #define PG8_STAGE(bufoff, gbase, voff) do { _Pragma("unroll") for (int _i = 0; _i < 2; ++_i) \
;         __builtin_amdgcn_global_load_lds((const unsigned*)((const char*)(gbase) + (voff)[_i]), (PG8_LAS unsigned*)(lds + (bufoff) + ldsw + _i * 8192), 16, 0, 0); } while (0)
; #define PG8_WAIT_V(n) asm volatile("s_waitcnt vmcnt(" #n ")" ::: "memory")
; #define PG8_WAIT_L(n) asm volatile("s_waitcnt lgkmcnt(" #n ")" ::: "memory")
; #define PG8_BAR __builtin_amdgcn_s_barrier()
; #define PG8_SCHED __builtin_amdgcn_sched_barrier(0)
;     ...
;             PG8_WAIT_V(8); PG8_WAIT_L(0); PG8_BAR; PG8_MMA(1, 0, At, B0); PG8_MMA(1, 1, At, B1); PG8_BAR; PG8_SCHED;
;             PG8_LDB(B0, 1, 0); PG8_LDB(B1, 1, 1); PG8_SCHED; PG8_LDA(At, 1, 0); PG8_STAGE(PG8_SA(0, 1), a2 + hstep, voffA);
;             PG8_WAIT_V(8); PG8_WAIT_L(0); PG8_BAR; PG8_MMA(0, 0, At, B0); PG8_MMA(0, 1, At, B1); PG8_BAR; PG8_SCHED;
;             PG8_LDA(At, 1, 1); PG8_STAGE(PG8_SB(1, 0), b3, voffB); PG8_STAGE(PG8_SB(1, 1), b3 + hstep, voffB); PG8_STAGE(PG8_SA(1, 0), a3, voffA);
;             PG8_WAIT_V(8); PG8_WAIT_L(0); PG8_BAR; PG8_MMA(1, 0, At, B0); PG8_MMA(1, 1, At, B1); PG8_BAR; PG8_SCHED;
.Lp1_cm_back:
	s_setprio 1
	s_waitcnt lgkmcnt(0)
	v_mfma_i32_16x16x64_i8 v[60:63], v[166:169], v[198:201], v[60:63]
	v_mfma_i32_16x16x64_i8 v[60:63], v[170:173], v[202:205], v[60:63]
	v_mfma_i32_16x16x64_i8 v[52:55], v[174:177], v[198:201], v[52:55]
	v_mfma_i32_16x16x64_i8 v[52:55], v[178:181], v[202:205], v[52:55]
	v_mfma_i32_16x16x64_i8 v[44:47], v[166:169], v[206:209], v[44:47]
	v_mfma_i32_16x16x64_i8 v[44:47], v[170:173], v[214:217], v[44:47]
	v_mfma_i32_16x16x64_i8 v[36:39], v[174:177], v[206:209], v[36:39]
	v_mfma_i32_16x16x64_i8 v[36:39], v[178:181], v[214:217], v[36:39]
	v_mfma_i32_16x16x64_i8 v[28:31], v[166:169], v[218:221], v[28:31]
	v_mfma_i32_16x16x64_i8 v[28:31], v[170:173], v[222:225], v[28:31]
	v_mfma_i32_16x16x64_i8 v[20:23], v[174:177], v[218:221], v[20:23]
	v_mfma_i32_16x16x64_i8 v[20:23], v[178:181], v[222:225], v[20:23]
	v_mfma_i32_16x16x64_i8 v[12:15], v[166:169], v[226:229], v[12:15]
	v_mfma_i32_16x16x64_i8 v[12:15], v[170:173], v[230:233], v[12:15]
	v_mfma_i32_16x16x64_i8 v[4:7], v[174:177], v[226:229], v[4:7]
	v_mfma_i32_16x16x64_i8 v[4:7], v[178:181], v[230:233], v[4:7]
	s_setprio 0
	s_setprio 1
	v_mfma_i32_16x16x64_i8 v[56:59], v[182:185], v[198:201], v[56:59]
	v_mfma_i32_16x16x64_i8 v[56:59], v[186:189], v[202:205], v[56:59]
	v_mfma_i32_16x16x64_i8 v[48:51], v[190:193], v[198:201], v[48:51]
	v_mfma_i32_16x16x64_i8 v[48:51], v[194:197], v[202:205], v[48:51]
	v_mfma_i32_16x16x64_i8 v[40:43], v[182:185], v[206:209], v[40:43]
	v_mfma_i32_16x16x64_i8 v[40:43], v[186:189], v[214:217], v[40:43]
	v_mfma_i32_16x16x64_i8 v[32:35], v[190:193], v[206:209], v[32:35]
	v_mfma_i32_16x16x64_i8 v[32:35], v[194:197], v[214:217], v[32:35]
	v_mfma_i32_16x16x64_i8 v[24:27], v[182:185], v[218:221], v[24:27]
	v_mfma_i32_16x16x64_i8 v[24:27], v[186:189], v[222:225], v[24:27]
	v_mfma_i32_16x16x64_i8 v[16:19], v[190:193], v[218:221], v[16:19]
	v_mfma_i32_16x16x64_i8 v[16:19], v[194:197], v[222:225], v[16:19]
	v_mfma_i32_16x16x64_i8 v[8:11], v[182:185], v[226:229], v[8:11]
	v_mfma_i32_16x16x64_i8 v[8:11], v[186:189], v[230:233], v[8:11]
	v_mfma_i32_16x16x64_i8 v[0:3], v[190:193], v[226:229], v[0:3]
	v_mfma_i32_16x16x64_i8 v[0:3], v[194:197], v[230:233], v[0:3]
	s_setprio 0
	s_barrier
	s_add_i32 s74, s74, 2
	s_add_u32 s50, s50, 0x100
	s_addc_u32 s51, s51, 0
	s_add_u32 s72, s72, 0x100
	s_addc_u32 s73, s73, 0
	s_cmp_gt_u32 s74, 13
	s_cbranch_scc1 .LBB0_251

; #define PG8_STAGE(bufoff, gbase, voff) do { _Pragma("unroll") for (int _i = 0; _i < 2; ++_i) \
;         __builtin_amdgcn_global_load_lds((const unsigned*)((const char*)(gbase) + (voff)[_i]), (PG8_LAS unsigned*)(lds + (bufoff) + ldsw + _i * 8192), 16, 0, 0); } while (0)
; #define PG8_WAIT_V(n) asm volatile("s_waitcnt vmcnt(" #n ")" ::: "memory")
; #define PG8_WAIT_L(n) asm volatile("s_waitcnt lgkmcnt(" #n ")" ::: "memory")
; #define PG8_BAR __builtin_amdgcn_s_barrier()
; #define PG8_SCHED __builtin_amdgcn_sched_barrier(0)
;     ...
;             PG8_LDB(B0, 0, 0); PG8_LDB(B1, 0, 1); PG8_SCHED; PG8_LDA(At, 0, 0); PG8_STAGE(PG8_SA(1, 1), a1 + hstep, voffA);
;             PG8_WAIT_V(8); PG8_WAIT_L(0); PG8_BAR; PG8_MMA(0, 0, At, B0); PG8_MMA(0, 1, At, B1); PG8_BAR; PG8_SCHED;
;             PG8_LDA(At, 0, 1); PG8_STAGE(PG8_SB(0, 0), b2, voffB); PG8_STAGE(PG8_SB(0, 1), b2 + hstep, voffB); PG8_STAGE(PG8_SA(0, 0), a2, voffA);
;             PG8_WAIT_V(8); PG8_WAIT_L(0); PG8_BAR; PG8_MMA(1, 0, At, B0); PG8_MMA(1, 1, At, B1); PG8_BAR; PG8_SCHED;
;             PG8_LDB(B0, 1, 0); PG8_LDB(B1, 1, 1); PG8_SCHED; PG8_LDA(At, 1, 0); PG8_STAGE(PG8_SA(0, 1), a2 + hstep, voffA);
.LBB0_335:
	ds_read_b128 v[128:131], v191
	ds_read_b128 v[132:135], v191 offset:1024
	ds_read_b128 v[136:139], v191 offset:2048
	ds_read_b128 v[140:143], v191 offset:3072
	ds_read_b128 v[144:147], v192
	ds_read_b128 v[148:151], v192 offset:1024
	ds_read_b128 v[168:171], v192 offset:2048
	ds_read_b128 v[172:175], v192 offset:3072
	s_add_u32 s33, s50, 0xffea0080
	s_addc_u32 s52, s51, -1
	s_cmpk_eq_i32 s72, 0x54
	s_cselect_b32 s55, s1, s52
	s_cselect_b32 s54, s0, s33
	s_cselect_b32 s53, s49, s35
	s_cselect_b32 s52, s48, s34
	v_lshl_add_u64 v[218:219], s[50:51], 0, v[160:161]
	s_add_i32 m0, s56, 0xc000
	ds_read_b128 v[176:179], v193
	ds_read_b128 v[180:183], v193 offset:1024
	ds_read_b128 v[184:187], v193 offset:2048
	ds_read_b128 v[196:199], v193 offset:3072
	ds_read_b128 v[200:203], v193 offset:4096
	ds_read_b128 v[204:207], v193 offset:5120
	ds_read_b128 v[208:211], v193 offset:6144
	ds_read_b128 v[214:217], v193 offset:7168
	global_load_lds_dwordx4 v[218:219], off
	v_lshl_add_u64 v[218:219], s[50:51], 0, v[162:163]
	s_add_i32 m0, s56, 0xe000
	s_nop 0
	global_load_lds_dwordx4 v[218:219], off
	s_waitcnt vmcnt(8)
	s_waitcnt lgkmcnt(0)
	s_barrier
	s_setprio 1
	s_waitcnt lgkmcnt(0)
	v_mfma_f32_16x16x32_bf16 v[124:127], v[128:131], v[176:179], v[124:127]
	v_mfma_f32_16x16x32_bf16 v[124:127], v[132:135], v[180:183], v[124:127]
	v_mfma_f32_16x16x32_bf16 v[120:123], v[136:139], v[176:179], v[120:123]
	v_mfma_f32_16x16x32_bf16 v[120:123], v[140:143], v[180:183], v[120:123]
	v_mfma_f32_16x16x32_bf16 v[108:111], v[128:131], v[184:187], v[108:111]
	v_mfma_f32_16x16x32_bf16 v[108:111], v[132:135], v[196:199], v[108:111]
	v_mfma_f32_16x16x32_bf16 v[104:107], v[136:139], v[184:187], v[104:107]
	v_mfma_f32_16x16x32_bf16 v[104:107], v[140:143], v[196:199], v[104:107]
	v_mfma_f32_16x16x32_bf16 v[92:95], v[128:131], v[200:203], v[92:95]
	v_mfma_f32_16x16x32_bf16 v[92:95], v[132:135], v[204:207], v[92:95]
	v_mfma_f32_16x16x32_bf16 v[88:91], v[136:139], v[200:203], v[88:91]
	v_mfma_f32_16x16x32_bf16 v[88:91], v[140:143], v[204:207], v[88:91]
	v_mfma_f32_16x16x32_bf16 v[76:79], v[128:131], v[208:211], v[76:79]
	v_mfma_f32_16x16x32_bf16 v[76:79], v[132:135], v[214:217], v[76:79]
	v_mfma_f32_16x16x32_bf16 v[72:75], v[136:139], v[208:211], v[72:75]
	v_mfma_f32_16x16x32_bf16 v[72:75], v[140:143], v[214:217], v[72:75]
	s_setprio 0
	s_setprio 1
	v_mfma_f32_16x16x32_bf16 v[116:119], v[144:147], v[176:179], v[116:119]
	v_mfma_f32_16x16x32_bf16 v[116:119], v[148:151], v[180:183], v[116:119]
	v_mfma_f32_16x16x32_bf16 v[112:115], v[168:171], v[176:179], v[112:115]
	v_mfma_f32_16x16x32_bf16 v[112:115], v[172:175], v[180:183], v[112:115]
	v_mfma_f32_16x16x32_bf16 v[100:103], v[144:147], v[184:187], v[100:103]
	v_mfma_f32_16x16x32_bf16 v[100:103], v[148:151], v[196:199], v[100:103]
	v_mfma_f32_16x16x32_bf16 v[96:99], v[168:171], v[184:187], v[96:99]
	v_mfma_f32_16x16x32_bf16 v[96:99], v[172:175], v[196:199], v[96:99]
	v_mfma_f32_16x16x32_bf16 v[84:87], v[144:147], v[200:203], v[84:87]
	v_mfma_f32_16x16x32_bf16 v[84:87], v[148:151], v[204:207], v[84:87]
	v_mfma_f32_16x16x32_bf16 v[80:83], v[168:171], v[200:203], v[80:83]
	v_mfma_f32_16x16x32_bf16 v[80:83], v[172:175], v[204:207], v[80:83]
	v_mfma_f32_16x16x32_bf16 v[68:71], v[144:147], v[208:211], v[68:71]
	v_mfma_f32_16x16x32_bf16 v[68:71], v[148:151], v[214:217], v[68:71]
	v_mfma_f32_16x16x32_bf16 v[64:67], v[168:171], v[208:211], v[64:67]
	v_mfma_f32_16x16x32_bf16 v[64:67], v[172:175], v[214:217], v[64:67]
	s_setprio 0
	s_barrier
	s_add_i32 s33, s66, s19
	v_lshl_add_u64 v[218:219], s[52:53], 0, v[154:155]
	s_mov_b32 m0, s33
	ds_read_b128 v[176:179], v193 offset:16384
	ds_read_b128 v[180:183], v193 offset:17408
	ds_read_b128 v[184:187], v193 offset:18432
	ds_read_b128 v[196:199], v193 offset:19456
	ds_read_b128 v[200:203], v193 offset:20480
	ds_read_b128 v[204:207], v193 offset:21504
	ds_read_b128 v[208:211], v193 offset:22528
	ds_read_b128 v[214:217], v193 offset:23552
	global_load_lds_dwordx4 v[218:219], off
	s_add_i32 m0, s33, 0x2000
	s_add_u32 s74, s52, 0x160000
	v_lshl_add_u64 v[220:221], s[52:53], 0, v[158:159]
	s_addc_u32 s75, s53, 0
	s_add_i32 s33, s67, s19
	global_load_lds_dwordx4 v[220:221], off
	v_lshl_add_u64 v[222:223], s[74:75], 0, v[154:155]
	s_mov_b32 m0, s33
	v_lshl_add_u64 v[224:225], s[54:55], 0, v[156:157]
	global_load_lds_dwordx4 v[222:223], off
	v_lshl_add_u64 v[222:223], s[74:75], 0, v[158:159]
	s_add_i32 m0, s33, 0x2000
	s_nop 0
	global_load_lds_dwordx4 v[222:223], off
	v_lshl_add_u64 v[222:223], s[54:55], 0, v[152:153]
	s_mov_b32 m0, s56
	s_nop 0
	global_load_lds_dwordx4 v[222:223], off
	s_mov_b32 m0, s57
	s_nop 0
	global_load_lds_dwordx4 v[224:225], off
	s_waitcnt vmcnt(8)
	s_waitcnt lgkmcnt(0)
	s_barrier
; #define PG8_STAGE(bufoff, gbase, voff) do { _Pragma("unroll") for (int _i = 0; _i < 2; ++_i) \
;         __builtin_amdgcn_global_load_lds((const unsigned*)((const char*)(gbase) + (voff)[_i]), (PG8_LAS unsigned*)(lds + (bufoff) + ldsw + _i * 8192), 16, 0, 0); } while (0)
; #define PG8_WAIT_V(n) asm volatile("s_waitcnt vmcnt(" #n ")" ::: "memory")
; #define PG8_WAIT_L(n) asm volatile("s_waitcnt lgkmcnt(" #n ")" ::: "memory")
; #define PG8_BAR __builtin_amdgcn_s_barrier()
; #define PG8_SCHED __builtin_amdgcn_sched_barrier(0)
;     ...
;             PG8_WAIT_V(8); PG8_WAIT_L(0); PG8_BAR; PG8_MMA(0, 0, At, B0); PG8_MMA(0, 1, At, B1); PG8_BAR; PG8_SCHED;
;             PG8_LDA(At, 0, 1); PG8_STAGE(PG8_SB(0, 0), b2, voffB); PG8_STAGE(PG8_SB(0, 1), b2 + hstep, voffB); PG8_STAGE(PG8_SA(0, 0), a2, voffA);
;             PG8_WAIT_V(8); PG8_WAIT_L(0); PG8_BAR; PG8_MMA(1, 0, At, B0); PG8_MMA(1, 1, At, B1); PG8_BAR; PG8_SCHED;
;             PG8_LDB(B0, 1, 0); PG8_LDB(B1, 1, 1); PG8_SCHED; PG8_LDA(At, 1, 0); PG8_STAGE(PG8_SA(0, 1), a2 + hstep, voffA);
;             PG8_WAIT_V(8); PG8_WAIT_L(0); PG8_BAR; PG8_MMA(0, 0, At, B0); PG8_MMA(0, 1, At, B1); PG8_BAR; PG8_SCHED;
	s_setprio 1
	s_waitcnt lgkmcnt(0)
	v_mfma_f32_16x16x32_bf16 v[60:63], v[128:131], v[176:179], v[60:63]
	v_mfma_f32_16x16x32_bf16 v[60:63], v[132:135], v[180:183], v[60:63]
	v_mfma_f32_16x16x32_bf16 v[56:59], v[136:139], v[176:179], v[56:59]
	v_mfma_f32_16x16x32_bf16 v[56:59], v[140:143], v[180:183], v[56:59]
	v_mfma_f32_16x16x32_bf16 v[44:47], v[128:131], v[184:187], v[44:47]
	v_mfma_f32_16x16x32_bf16 v[44:47], v[132:135], v[196:199], v[44:47]
	v_mfma_f32_16x16x32_bf16 v[40:43], v[136:139], v[184:187], v[40:43]
	v_mfma_f32_16x16x32_bf16 v[40:43], v[140:143], v[196:199], v[40:43]
	v_mfma_f32_16x16x32_bf16 v[28:31], v[128:131], v[200:203], v[28:31]
	v_mfma_f32_16x16x32_bf16 v[28:31], v[132:135], v[204:207], v[28:31]
	v_mfma_f32_16x16x32_bf16 v[24:27], v[136:139], v[200:203], v[24:27]
	v_mfma_f32_16x16x32_bf16 v[24:27], v[140:143], v[204:207], v[24:27]
	v_mfma_f32_16x16x32_bf16 v[12:15], v[128:131], v[208:211], v[12:15]
	v_mfma_f32_16x16x32_bf16 v[12:15], v[132:135], v[214:217], v[12:15]
	v_mfma_f32_16x16x32_bf16 v[8:11], v[136:139], v[208:211], v[8:11]
	v_mfma_f32_16x16x32_bf16 v[8:11], v[140:143], v[214:217], v[8:11]
	s_setprio 0
	s_setprio 1
	v_mfma_f32_16x16x32_bf16 v[52:55], v[144:147], v[176:179], v[52:55]
	v_mfma_f32_16x16x32_bf16 v[52:55], v[148:151], v[180:183], v[52:55]
	v_mfma_f32_16x16x32_bf16 v[48:51], v[168:171], v[176:179], v[48:51]
	v_mfma_f32_16x16x32_bf16 v[48:51], v[172:175], v[180:183], v[48:51]
	v_mfma_f32_16x16x32_bf16 v[36:39], v[144:147], v[184:187], v[36:39]
	v_mfma_f32_16x16x32_bf16 v[36:39], v[148:151], v[196:199], v[36:39]
	v_mfma_f32_16x16x32_bf16 v[32:35], v[168:171], v[184:187], v[32:35]
	v_mfma_f32_16x16x32_bf16 v[32:35], v[172:175], v[196:199], v[32:35]
	v_mfma_f32_16x16x32_bf16 v[20:23], v[144:147], v[200:203], v[20:23]
	v_mfma_f32_16x16x32_bf16 v[20:23], v[148:151], v[204:207], v[20:23]
	v_mfma_f32_16x16x32_bf16 v[16:19], v[168:171], v[200:203], v[16:19]
	v_mfma_f32_16x16x32_bf16 v[16:19], v[172:175], v[204:207], v[16:19]
	v_mfma_f32_16x16x32_bf16 v[4:7], v[144:147], v[208:211], v[4:7]
	v_mfma_f32_16x16x32_bf16 v[4:7], v[148:151], v[214:217], v[4:7]
	v_mfma_f32_16x16x32_bf16 v[0:3], v[168:171], v[208:211], v[0:3]
	v_mfma_f32_16x16x32_bf16 v[0:3], v[172:175], v[214:217], v[0:3]
	s_setprio 0
	s_barrier
	s_add_i32 s33, 0, 0x18000
	s_add_i32 s73, 0, 0x1c000
	v_add_u32_e32 v140, s33, v189
	v_add_u32_e32 v172, s73, v189
	ds_read_b128 v[128:131], v140
	ds_read_b128 v[132:135], v140 offset:1024
	ds_read_b128 v[136:139], v140 offset:2048
	ds_read_b128 v[140:143], v140 offset:3072
	ds_read_b128 v[144:147], v172
	ds_read_b128 v[148:151], v172 offset:1024
	ds_read_b128 v[168:171], v172 offset:2048
	ds_read_b128 v[172:175], v172 offset:3072
	s_add_u32 s54, s54, 0x160000
	s_addc_u32 s55, s55, 0
	s_mov_b32 m0, s58
	v_lshl_add_u64 v[226:227], s[54:55], 0, v[152:153]
	ds_read_b128 v[176:179], v193 offset:32768
	ds_read_b128 v[180:183], v193 offset:33792
	ds_read_b128 v[184:187], v193 offset:34816
	ds_read_b128 v[196:199], v193 offset:35840
	ds_read_b128 v[200:203], v193 offset:36864
	ds_read_b128 v[204:207], v193 offset:37888
	ds_read_b128 v[208:211], v193 offset:38912
	ds_read_b128 v[214:217], v193 offset:39936
	global_load_lds_dwordx4 v[226:227], off
	v_lshl_add_u64 v[226:227], s[54:55], 0, v[156:157]
	s_mov_b32 m0, s59
	s_nop 0
	global_load_lds_dwordx4 v[226:227], off
	s_waitcnt vmcnt(8)
	s_waitcnt lgkmcnt(0)
	s_barrier
	s_setprio 1
	s_waitcnt lgkmcnt(0)
	v_mfma_f32_16x16x32_bf16 v[124:127], v[128:131], v[176:179], v[124:127]
	v_mfma_f32_16x16x32_bf16 v[124:127], v[132:135], v[180:183], v[124:127]
	v_mfma_f32_16x16x32_bf16 v[120:123], v[136:139], v[176:179], v[120:123]
	v_mfma_f32_16x16x32_bf16 v[120:123], v[140:143], v[180:183], v[120:123]
	v_mfma_f32_16x16x32_bf16 v[108:111], v[128:131], v[184:187], v[108:111]
	v_mfma_f32_16x16x32_bf16 v[108:111], v[132:135], v[196:199], v[108:111]
	v_mfma_f32_16x16x32_bf16 v[104:107], v[136:139], v[184:187], v[104:107]
	v_mfma_f32_16x16x32_bf16 v[104:107], v[140:143], v[196:199], v[104:107]
	v_mfma_f32_16x16x32_bf16 v[92:95], v[128:131], v[200:203], v[92:95]
	v_mfma_f32_16x16x32_bf16 v[92:95], v[132:135], v[204:207], v[92:95]
	v_mfma_f32_16x16x32_bf16 v[88:91], v[136:139], v[200:203], v[88:91]
	v_mfma_f32_16x16x32_bf16 v[88:91], v[140:143], v[204:207], v[88:91]
	v_mfma_f32_16x16x32_bf16 v[76:79], v[128:131], v[208:211], v[76:79]
	v_mfma_f32_16x16x32_bf16 v[76:79], v[132:135], v[214:217], v[76:79]
	v_mfma_f32_16x16x32_bf16 v[72:75], v[136:139], v[208:211], v[72:75]
	v_mfma_f32_16x16x32_bf16 v[72:75], v[140:143], v[214:217], v[72:75]
	s_setprio 0
	s_setprio 1
	v_mfma_f32_16x16x32_bf16 v[116:119], v[144:147], v[176:179], v[116:119]
	v_mfma_f32_16x16x32_bf16 v[116:119], v[148:151], v[180:183], v[116:119]
	v_mfma_f32_16x16x32_bf16 v[112:115], v[168:171], v[176:179], v[112:115]
	v_mfma_f32_16x16x32_bf16 v[112:115], v[172:175], v[180:183], v[112:115]
	v_mfma_f32_16x16x32_bf16 v[100:103], v[144:147], v[184:187], v[100:103]
	v_mfma_f32_16x16x32_bf16 v[100:103], v[148:151], v[196:199], v[100:103]
	v_mfma_f32_16x16x32_bf16 v[96:99], v[168:171], v[184:187], v[96:99]
	v_mfma_f32_16x16x32_bf16 v[96:99], v[172:175], v[196:199], v[96:99]
	v_mfma_f32_16x16x32_bf16 v[84:87], v[144:147], v[200:203], v[84:87]
	v_mfma_f32_16x16x32_bf16 v[84:87], v[148:151], v[204:207], v[84:87]
	v_mfma_f32_16x16x32_bf16 v[80:83], v[168:171], v[200:203], v[80:83]
	v_mfma_f32_16x16x32_bf16 v[80:83], v[172:175], v[204:207], v[80:83]
	v_mfma_f32_16x16x32_bf16 v[68:71], v[144:147], v[208:211], v[68:71]
	v_mfma_f32_16x16x32_bf16 v[68:71], v[148:151], v[214:217], v[68:71]
	v_mfma_f32_16x16x32_bf16 v[64:67], v[168:171], v[208:211], v[64:67]
	v_mfma_f32_16x16x32_bf16 v[64:67], v[172:175], v[214:217], v[64:67]
	s_setprio 0
	s_barrier
; #define PG8_STAGE(bufoff, gbase, voff) do { _Pragma("unroll") for (int _i = 0; _i < 2; ++_i) \
;         __builtin_amdgcn_global_load_lds((const unsigned*)((const char*)(gbase) + (voff)[_i]), (PG8_LAS unsigned*)(lds + (bufoff) + ldsw + _i * 8192), 16, 0, 0); } while (0)
; #define PG8_WAIT_V(n) asm volatile("s_waitcnt vmcnt(" #n ")" ::: "memory")
; #define PG8_WAIT_L(n) asm volatile("s_waitcnt lgkmcnt(" #n ")" ::: "memory")
; #define PG8_BAR __builtin_amdgcn_s_barrier()
; #define PG8_SCHED __builtin_amdgcn_sched_barrier(0)
;     ...
;             PG8_LDB(B0, 1, 0); PG8_LDB(B1, 1, 1); PG8_SCHED; PG8_LDA(At, 1, 0); PG8_STAGE(PG8_SA(0, 1), a2 + hstep, voffA);
;             PG8_WAIT_V(8); PG8_WAIT_L(0); PG8_BAR; PG8_MMA(0, 0, At, B0); PG8_MMA(0, 1, At, B1); PG8_BAR; PG8_SCHED;
;             PG8_LDA(At, 1, 1); PG8_STAGE(PG8_SB(1, 0), b3, voffB); PG8_STAGE(PG8_SB(1, 1), b3 + hstep, voffB); PG8_STAGE(PG8_SA(1, 0), a3, voffA);
;             PG8_WAIT_V(8); PG8_WAIT_L(0); PG8_BAR; PG8_MMA(1, 0, At, B0); PG8_MMA(1, 1, At, B1); PG8_BAR; PG8_SCHED;
	s_add_i32 s33, s33, s19
	v_lshl_add_u64 v[218:219], v[218:219], 0, s[24:25]
	s_mov_b32 m0, s33
	ds_read_b128 v[176:179], v193 offset:49152
	ds_read_b128 v[180:183], v193 offset:50176
	ds_read_b128 v[184:187], v193 offset:51200
	ds_read_b128 v[196:199], v193 offset:52224
	ds_read_b128 v[200:203], v193 offset:53248
	ds_read_b128 v[204:207], v193 offset:54272
	ds_read_b128 v[208:211], v193 offset:55296
	ds_read_b128 v[214:217], v193 offset:56320
	global_load_lds_dwordx4 v[218:219], off
	s_add_i32 m0, s33, 0x2000
	s_add_u32 s52, s52, 0x160080
	v_lshl_add_u64 v[218:219], v[220:221], 0, s[24:25]
	s_addc_u32 s53, s53, 0
	s_add_i32 s33, s73, s19
	global_load_lds_dwordx4 v[218:219], off
	v_lshl_add_u64 v[218:219], s[52:53], 0, v[154:155]
	s_mov_b32 m0, s33
	s_nop 0
	global_load_lds_dwordx4 v[218:219], off
	v_lshl_add_u64 v[218:219], s[52:53], 0, v[158:159]
	s_add_i32 m0, s33, 0x2000
	s_nop 0
	global_load_lds_dwordx4 v[218:219], off
	v_lshl_add_u64 v[218:219], v[222:223], 0, s[24:25]
	s_mov_b32 m0, s61
	s_nop 0
	global_load_lds_dwordx4 v[218:219], off
	v_lshl_add_u64 v[218:219], v[224:225], 0, s[24:25]
	s_mov_b32 m0, s62
	s_nop 0
	global_load_lds_dwordx4 v[218:219], off
	s_waitcnt vmcnt(8)
	s_waitcnt lgkmcnt(0)
	s_barrier
	s_setprio 1
	s_waitcnt lgkmcnt(0)
	v_mfma_f32_16x16x32_bf16 v[60:63], v[128:131], v[176:179], v[60:63]
	v_mfma_f32_16x16x32_bf16 v[60:63], v[132:135], v[180:183], v[60:63]
	v_mfma_f32_16x16x32_bf16 v[56:59], v[136:139], v[176:179], v[56:59]
	v_mfma_f32_16x16x32_bf16 v[56:59], v[140:143], v[180:183], v[56:59]
	v_mfma_f32_16x16x32_bf16 v[44:47], v[128:131], v[184:187], v[44:47]
	v_mfma_f32_16x16x32_bf16 v[44:47], v[132:135], v[196:199], v[44:47]
	v_mfma_f32_16x16x32_bf16 v[40:43], v[136:139], v[184:187], v[40:43]
	v_mfma_f32_16x16x32_bf16 v[40:43], v[140:143], v[196:199], v[40:43]
	v_mfma_f32_16x16x32_bf16 v[28:31], v[128:131], v[200:203], v[28:31]
	v_mfma_f32_16x16x32_bf16 v[28:31], v[132:135], v[204:207], v[28:31]
	v_mfma_f32_16x16x32_bf16 v[24:27], v[136:139], v[200:203], v[24:27]
	v_mfma_f32_16x16x32_bf16 v[24:27], v[140:143], v[204:207], v[24:27]
	v_mfma_f32_16x16x32_bf16 v[12:15], v[128:131], v[208:211], v[12:15]
	v_mfma_f32_16x16x32_bf16 v[12:15], v[132:135], v[214:217], v[12:15]
	v_mfma_f32_16x16x32_bf16 v[8:11], v[136:139], v[208:211], v[8:11]
	v_mfma_f32_16x16x32_bf16 v[8:11], v[140:143], v[214:217], v[8:11]
	s_setprio 0
	s_setprio 1
	v_mfma_f32_16x16x32_bf16 v[52:55], v[144:147], v[176:179], v[52:55]
	v_mfma_f32_16x16x32_bf16 v[52:55], v[148:151], v[180:183], v[52:55]
	v_mfma_f32_16x16x32_bf16 v[48:51], v[168:171], v[176:179], v[48:51]
	v_mfma_f32_16x16x32_bf16 v[48:51], v[172:175], v[180:183], v[48:51]
	v_mfma_f32_16x16x32_bf16 v[36:39], v[144:147], v[184:187], v[36:39]
	v_mfma_f32_16x16x32_bf16 v[36:39], v[148:151], v[196:199], v[36:39]
	v_mfma_f32_16x16x32_bf16 v[32:35], v[168:171], v[184:187], v[32:35]
	v_mfma_f32_16x16x32_bf16 v[32:35], v[172:175], v[196:199], v[32:35]
	v_mfma_f32_16x16x32_bf16 v[20:23], v[144:147], v[200:203], v[20:23]
	v_mfma_f32_16x16x32_bf16 v[20:23], v[148:151], v[204:207], v[20:23]
	v_mfma_f32_16x16x32_bf16 v[16:19], v[168:171], v[200:203], v[16:19]
	v_mfma_f32_16x16x32_bf16 v[16:19], v[172:175], v[204:207], v[16:19]
	v_mfma_f32_16x16x32_bf16 v[4:7], v[144:147], v[208:211], v[4:7]
	v_mfma_f32_16x16x32_bf16 v[4:7], v[148:151], v[214:217], v[4:7]
	v_mfma_f32_16x16x32_bf16 v[0:3], v[168:171], v[208:211], v[0:3]
	v_mfma_f32_16x16x32_bf16 v[0:3], v[172:175], v[214:217], v[0:3]
	s_setprio 0
	s_barrier
	s_add_i32 s72, s72, 2
	s_add_u32 s50, s50, 0x100
	s_addc_u32 s51, s51, 0
	s_add_u32 s34, s34, 0x100
	s_addc_u32 s35, s35, 0
	s_cmpk_gt_u32 s72, 0x55
	s_cbranch_scc0 .LBB0_335
	s_and_b64 vcc, exec, s[44:45]
	s_cbranch_vccz .LBB0_338
	s_barrier

; #define PG8_STAGE(bufoff, gbase, voff) do { _Pragma("unroll") for (int _i = 0; _i < 2; ++_i) \
;         __builtin_amdgcn_global_load_lds((const unsigned*)((const char*)(gbase) + (voff)[_i]), (PG8_LAS unsigned*)(lds + (bufoff) + ldsw + _i * 8192), 16, 0, 0); } while (0)
; #define PG8_WAIT_V(n) asm volatile("s_waitcnt vmcnt(" #n ")" ::: "memory")
; #define PG8_WAIT_L(n) asm volatile("s_waitcnt lgkmcnt(" #n ")" ::: "memory")
; #define PG8_BAR __builtin_amdgcn_s_barrier()
; #define PG8_SCHED __builtin_amdgcn_sched_barrier(0)
;     ...
;             PG8_LDB(B0, 0, 0); PG8_LDB(B1, 0, 1); PG8_SCHED; PG8_LDA(At, 0, 0); PG8_STAGE(PG8_SA(1, 1), a1 + hstep, voffA);
;             PG8_WAIT_V(8); PG8_WAIT_L(0); PG8_BAR; PG8_MMA(0, 0, At, B0); PG8_MMA(0, 1, At, B1); PG8_BAR; PG8_SCHED;
;             PG8_LDA(At, 0, 1); PG8_STAGE(PG8_SB(0, 0), b2, voffB); PG8_STAGE(PG8_SB(0, 1), b2 + hstep, voffB); PG8_STAGE(PG8_SA(0, 0), a2, voffA);
;             PG8_WAIT_V(8); PG8_WAIT_L(0); PG8_BAR; PG8_MMA(1, 0, At, B0); PG8_MMA(1, 1, At, B1); PG8_BAR; PG8_SCHED;
;             PG8_LDB(B0, 1, 0); PG8_LDB(B1, 1, 1); PG8_SCHED; PG8_LDA(At, 1, 0); PG8_STAGE(PG8_SA(0, 1), a2 + hstep, voffA);
;             PG8_WAIT_V(8); PG8_WAIT_L(0); PG8_BAR; PG8_MMA(0, 0, At, B0); PG8_MMA(0, 1, At, B1); PG8_BAR; PG8_SCHED;
.LBB0_432:
	v_add_u32_e32 v142, s91, v205
	v_add_u32_e32 v146, s92, v205
	ds_read_b128 v[130:133], v142
	ds_read_b128 v[134:137], v142 offset:1024
	s_waitcnt lgkmcnt(0)
	ds_read_b128 v[138:141], v142 offset:2048
	ds_read_b128 v[142:145], v142 offset:3072
	ds_read_b128 v[188:191], v146
	ds_read_b128 v[192:195], v146 offset:1024
	ds_read_b128 v[196:199], v146 offset:2048
	ds_read_b128 v[200:203], v146 offset:3072
	s_add_u32 s33, s70, 0xfff80080
	s_addc_u32 s74, s71, -1
	s_and_b64 s[72:73], s[72:73], exec
	s_cselect_b32 s75, s18, s74
	s_cselect_b32 s74, s19, s33
	s_cselect_b32 s73, s34, s61
	s_cselect_b32 s72, s35, s10
	v_lshl_add_u64 v[146:147], s[70:71], 0, v[162:163]
	s_add_i32 m0, s69, 0xc000
	ds_read_b128 v[214:217], v159
	ds_read_b128 v[218:221], v159 offset:1024
	ds_read_b128 v[222:225], v159 offset:2048
	ds_read_b128 v[226:229], v159 offset:3072
	ds_read_b128 v[230:233], v159 offset:4096
	ds_read_b128 v[234:237], v159 offset:5120
	ds_read_b128 v[238:241], v159 offset:6144
	ds_read_b128 v[242:245], v159 offset:7168
	global_load_lds_dwordx4 v[146:147], off
	v_lshl_add_u64 v[146:147], s[70:71], 0, v[164:165]
	s_add_i32 m0, s69, 0xe000
	s_nop 0
	global_load_lds_dwordx4 v[146:147], off
	s_waitcnt vmcnt(8)
	s_waitcnt lgkmcnt(0)
	s_barrier
	s_setprio 1
	s_waitcnt lgkmcnt(0)
	v_mfma_f32_16x16x32_bf16 v[124:127], v[130:133], v[214:217], v[124:127]
	v_mfma_f32_16x16x32_bf16 v[124:127], v[134:137], v[218:221], v[124:127]
	v_mfma_f32_16x16x32_bf16 v[120:123], v[138:141], v[214:217], v[120:123]
	v_mfma_f32_16x16x32_bf16 v[120:123], v[142:145], v[218:221], v[120:123]
	v_mfma_f32_16x16x32_bf16 v[108:111], v[130:133], v[222:225], v[108:111]
	v_mfma_f32_16x16x32_bf16 v[108:111], v[134:137], v[226:229], v[108:111]
	v_mfma_f32_16x16x32_bf16 v[104:107], v[138:141], v[222:225], v[104:107]
	v_mfma_f32_16x16x32_bf16 v[104:107], v[142:145], v[226:229], v[104:107]
	v_mfma_f32_16x16x32_bf16 v[92:95], v[130:133], v[230:233], v[92:95]
	v_mfma_f32_16x16x32_bf16 v[92:95], v[134:137], v[234:237], v[92:95]
	v_mfma_f32_16x16x32_bf16 v[88:91], v[138:141], v[230:233], v[88:91]
	v_mfma_f32_16x16x32_bf16 v[88:91], v[142:145], v[234:237], v[88:91]
	v_mfma_f32_16x16x32_bf16 v[76:79], v[130:133], v[238:241], v[76:79]
	v_mfma_f32_16x16x32_bf16 v[76:79], v[134:137], v[242:245], v[76:79]
	v_mfma_f32_16x16x32_bf16 v[72:75], v[138:141], v[238:241], v[72:75]
	v_mfma_f32_16x16x32_bf16 v[72:75], v[142:145], v[242:245], v[72:75]
	s_setprio 0
	s_setprio 1
	v_mfma_f32_16x16x32_bf16 v[116:119], v[188:191], v[214:217], v[116:119]
	v_mfma_f32_16x16x32_bf16 v[116:119], v[192:195], v[218:221], v[116:119]
	v_mfma_f32_16x16x32_bf16 v[112:115], v[196:199], v[214:217], v[112:115]
	v_mfma_f32_16x16x32_bf16 v[112:115], v[200:203], v[218:221], v[112:115]
	v_mfma_f32_16x16x32_bf16 v[100:103], v[188:191], v[222:225], v[100:103]
	v_mfma_f32_16x16x32_bf16 v[100:103], v[192:195], v[226:229], v[100:103]
	v_mfma_f32_16x16x32_bf16 v[96:99], v[196:199], v[222:225], v[96:99]
	v_mfma_f32_16x16x32_bf16 v[96:99], v[200:203], v[226:229], v[96:99]
	v_mfma_f32_16x16x32_bf16 v[84:87], v[188:191], v[230:233], v[84:87]
	v_mfma_f32_16x16x32_bf16 v[84:87], v[192:195], v[234:237], v[84:87]
	v_mfma_f32_16x16x32_bf16 v[80:83], v[196:199], v[230:233], v[80:83]
	v_mfma_f32_16x16x32_bf16 v[80:83], v[200:203], v[234:237], v[80:83]
	v_mfma_f32_16x16x32_bf16 v[68:71], v[188:191], v[238:241], v[68:71]
	v_mfma_f32_16x16x32_bf16 v[68:71], v[192:195], v[242:245], v[68:71]
	v_mfma_f32_16x16x32_bf16 v[64:67], v[196:199], v[238:241], v[64:67]
	v_mfma_f32_16x16x32_bf16 v[64:67], v[200:203], v[242:245], v[64:67]
	s_setprio 0
	s_barrier
	s_add_i32 s33, s91, s82
	v_lshl_add_u64 v[146:147], s[72:73], 0, v[150:151]
	s_mov_b32 m0, s33
	ds_read_b128 v[214:217], v159 offset:16384
	ds_read_b128 v[218:221], v159 offset:17408
	ds_read_b128 v[222:225], v159 offset:18432
	ds_read_b128 v[226:229], v159 offset:19456
	ds_read_b128 v[230:233], v159 offset:20480
	ds_read_b128 v[234:237], v159 offset:21504
	ds_read_b128 v[238:241], v159 offset:22528
	ds_read_b128 v[242:245], v159 offset:23552
	global_load_lds_dwordx4 v[146:147], off
	s_add_i32 m0, s33, 0x2000
	s_add_u32 s94, s72, 0x80000
	v_lshl_add_u64 v[246:247], s[72:73], 0, v[154:155]
	s_addc_u32 s95, s73, 0
	s_add_i32 s33, s92, s82
	global_load_lds_dwordx4 v[246:247], off
	v_lshl_add_u64 v[248:249], s[94:95], 0, v[150:151]
	s_mov_b32 m0, s33
	v_lshl_add_u64 v[250:251], s[74:75], 0, v[152:153]
	global_load_lds_dwordx4 v[248:249], off
	v_lshl_add_u64 v[248:249], s[94:95], 0, v[154:155]
	s_add_i32 m0, s33, 0x2000
	s_nop 0
	global_load_lds_dwordx4 v[248:249], off
	v_lshl_add_u64 v[248:249], s[74:75], 0, v[148:149]
	s_mov_b32 m0, s69
	s_nop 0
	global_load_lds_dwordx4 v[248:249], off
	s_mov_b32 m0, s83
	s_nop 0
	global_load_lds_dwordx4 v[250:251], off
	s_waitcnt vmcnt(8)
	s_waitcnt lgkmcnt(0)
	s_barrier
; #define PG8_STAGE(bufoff, gbase, voff) do { _Pragma("unroll") for (int _i = 0; _i < 2; ++_i) \
;         __builtin_amdgcn_global_load_lds((const unsigned*)((const char*)(gbase) + (voff)[_i]), (PG8_LAS unsigned*)(lds + (bufoff) + ldsw + _i * 8192), 16, 0, 0); } while (0)
; #define PG8_WAIT_V(n) asm volatile("s_waitcnt vmcnt(" #n ")" ::: "memory")
; #define PG8_WAIT_L(n) asm volatile("s_waitcnt lgkmcnt(" #n ")" ::: "memory")
; #define PG8_BAR __builtin_amdgcn_s_barrier()
; #define PG8_SCHED __builtin_amdgcn_sched_barrier(0)
;     ...
;             PG8_LDA(At, 0, 1); PG8_STAGE(PG8_SB(0, 0), b2, voffB); PG8_STAGE(PG8_SB(0, 1), b2 + hstep, voffB); PG8_STAGE(PG8_SA(0, 0), a2, voffA);
;             PG8_WAIT_V(8); PG8_WAIT_L(0); PG8_BAR; PG8_MMA(1, 0, At, B0); PG8_MMA(1, 1, At, B1); PG8_BAR; PG8_SCHED;
;             PG8_LDB(B0, 1, 0); PG8_LDB(B1, 1, 1); PG8_SCHED; PG8_LDA(At, 1, 0); PG8_STAGE(PG8_SA(0, 1), a2 + hstep, voffA);
;             PG8_WAIT_V(8); PG8_WAIT_L(0); PG8_BAR; PG8_MMA(0, 0, At, B0); PG8_MMA(0, 1, At, B1); PG8_BAR; PG8_SCHED;
;             PG8_LDA(At, 1, 1); PG8_STAGE(PG8_SB(1, 0), b3, voffB); PG8_STAGE(PG8_SB(1, 1), b3 + hstep, voffB); PG8_STAGE(PG8_SA(1, 0), a3, voffA);
	s_setprio 1
	s_waitcnt lgkmcnt(0)
	v_mfma_f32_16x16x32_bf16 v[60:63], v[130:133], v[214:217], v[60:63]
	v_mfma_f32_16x16x32_bf16 v[60:63], v[134:137], v[218:221], v[60:63]
	v_mfma_f32_16x16x32_bf16 v[56:59], v[138:141], v[214:217], v[56:59]
	v_mfma_f32_16x16x32_bf16 v[56:59], v[142:145], v[218:221], v[56:59]
	v_mfma_f32_16x16x32_bf16 v[44:47], v[130:133], v[222:225], v[44:47]
	v_mfma_f32_16x16x32_bf16 v[44:47], v[134:137], v[226:229], v[44:47]
	v_mfma_f32_16x16x32_bf16 v[40:43], v[138:141], v[222:225], v[40:43]
	v_mfma_f32_16x16x32_bf16 v[40:43], v[142:145], v[226:229], v[40:43]
	v_mfma_f32_16x16x32_bf16 v[28:31], v[130:133], v[230:233], v[28:31]
	v_mfma_f32_16x16x32_bf16 v[28:31], v[134:137], v[234:237], v[28:31]
	v_mfma_f32_16x16x32_bf16 v[24:27], v[138:141], v[230:233], v[24:27]
	v_mfma_f32_16x16x32_bf16 v[24:27], v[142:145], v[234:237], v[24:27]
	v_mfma_f32_16x16x32_bf16 v[12:15], v[130:133], v[238:241], v[12:15]
	v_mfma_f32_16x16x32_bf16 v[12:15], v[134:137], v[242:245], v[12:15]
	v_mfma_f32_16x16x32_bf16 v[8:11], v[138:141], v[238:241], v[8:11]
	v_mfma_f32_16x16x32_bf16 v[8:11], v[142:145], v[242:245], v[8:11]
	s_setprio 0
	s_setprio 1
	v_mfma_f32_16x16x32_bf16 v[52:55], v[188:191], v[214:217], v[52:55]
	v_mfma_f32_16x16x32_bf16 v[52:55], v[192:195], v[218:221], v[52:55]
	v_mfma_f32_16x16x32_bf16 v[48:51], v[196:199], v[214:217], v[48:51]
	v_mfma_f32_16x16x32_bf16 v[48:51], v[200:203], v[218:221], v[48:51]
	v_mfma_f32_16x16x32_bf16 v[36:39], v[188:191], v[222:225], v[36:39]
	v_mfma_f32_16x16x32_bf16 v[36:39], v[192:195], v[226:229], v[36:39]
	v_mfma_f32_16x16x32_bf16 v[32:35], v[196:199], v[222:225], v[32:35]
	v_mfma_f32_16x16x32_bf16 v[32:35], v[200:203], v[226:229], v[32:35]
	v_mfma_f32_16x16x32_bf16 v[20:23], v[188:191], v[230:233], v[20:23]
	v_mfma_f32_16x16x32_bf16 v[20:23], v[192:195], v[234:237], v[20:23]
	v_mfma_f32_16x16x32_bf16 v[16:19], v[196:199], v[230:233], v[16:19]
	v_mfma_f32_16x16x32_bf16 v[16:19], v[200:203], v[234:237], v[16:19]
	v_mfma_f32_16x16x32_bf16 v[4:7], v[188:191], v[238:241], v[4:7]
	v_mfma_f32_16x16x32_bf16 v[4:7], v[192:195], v[242:245], v[4:7]
	v_mfma_f32_16x16x32_bf16 v[0:3], v[196:199], v[238:241], v[0:3]
	v_mfma_f32_16x16x32_bf16 v[0:3], v[200:203], v[242:245], v[0:3]
	s_setprio 0
	s_barrier
	s_add_i32 s33, 0, 0x18000
	s_add_i32 s94, 0, 0x1c000
	v_add_u32_e32 v142, s33, v205
	v_add_u32_e32 v156, s94, v205
	ds_read_b128 v[130:133], v142
	ds_read_b128 v[134:137], v142 offset:1024
	ds_read_b128 v[138:141], v142 offset:2048
	ds_read_b128 v[142:145], v142 offset:3072
	ds_read_b128 v[188:191], v156
	ds_read_b128 v[192:195], v156 offset:1024
	ds_read_b128 v[196:199], v156 offset:2048
	ds_read_b128 v[200:203], v156 offset:3072
	s_add_u32 s74, s74, 0x80000
	s_addc_u32 s75, s75, 0
	s_mov_b32 m0, s84
	v_lshl_add_u64 v[252:253], s[74:75], 0, v[148:149]
	ds_read_b128 v[214:217], v159 offset:32768
	ds_read_b128 v[218:221], v159 offset:33792
	ds_read_b128 v[222:225], v159 offset:34816
	ds_read_b128 v[226:229], v159 offset:35840
	ds_read_b128 v[230:233], v159 offset:36864
	ds_read_b128 v[234:237], v159 offset:37888
	ds_read_b128 v[238:241], v159 offset:38912
	ds_read_b128 v[242:245], v159 offset:39936
	global_load_lds_dwordx4 v[252:253], off
	v_lshl_add_u64 v[252:253], s[74:75], 0, v[152:153]
	s_mov_b32 m0, s85
	s_nop 0
	global_load_lds_dwordx4 v[252:253], off
	s_waitcnt vmcnt(8)
	s_waitcnt lgkmcnt(0)
	s_barrier
	s_setprio 1
	s_waitcnt lgkmcnt(0)
	v_mfma_f32_16x16x32_bf16 v[124:127], v[130:133], v[214:217], v[124:127]
	v_mfma_f32_16x16x32_bf16 v[124:127], v[134:137], v[218:221], v[124:127]
	v_mfma_f32_16x16x32_bf16 v[120:123], v[138:141], v[214:217], v[120:123]
	v_mfma_f32_16x16x32_bf16 v[120:123], v[142:145], v[218:221], v[120:123]
	v_mfma_f32_16x16x32_bf16 v[108:111], v[130:133], v[222:225], v[108:111]
	v_mfma_f32_16x16x32_bf16 v[108:111], v[134:137], v[226:229], v[108:111]
	v_mfma_f32_16x16x32_bf16 v[104:107], v[138:141], v[222:225], v[104:107]
	v_mfma_f32_16x16x32_bf16 v[104:107], v[142:145], v[226:229], v[104:107]
	v_mfma_f32_16x16x32_bf16 v[92:95], v[130:133], v[230:233], v[92:95]
	v_mfma_f32_16x16x32_bf16 v[92:95], v[134:137], v[234:237], v[92:95]
	v_mfma_f32_16x16x32_bf16 v[88:91], v[138:141], v[230:233], v[88:91]
	v_mfma_f32_16x16x32_bf16 v[88:91], v[142:145], v[234:237], v[88:91]
	v_mfma_f32_16x16x32_bf16 v[76:79], v[130:133], v[238:241], v[76:79]
	v_mfma_f32_16x16x32_bf16 v[76:79], v[134:137], v[242:245], v[76:79]
	v_mfma_f32_16x16x32_bf16 v[72:75], v[138:141], v[238:241], v[72:75]
	v_mfma_f32_16x16x32_bf16 v[72:75], v[142:145], v[242:245], v[72:75]
	s_setprio 0
	s_setprio 1
	v_mfma_f32_16x16x32_bf16 v[116:119], v[188:191], v[214:217], v[116:119]
	v_mfma_f32_16x16x32_bf16 v[116:119], v[192:195], v[218:221], v[116:119]
	v_mfma_f32_16x16x32_bf16 v[112:115], v[196:199], v[214:217], v[112:115]
	v_mfma_f32_16x16x32_bf16 v[112:115], v[200:203], v[218:221], v[112:115]
	v_mfma_f32_16x16x32_bf16 v[100:103], v[188:191], v[222:225], v[100:103]
	v_mfma_f32_16x16x32_bf16 v[100:103], v[192:195], v[226:229], v[100:103]
	v_mfma_f32_16x16x32_bf16 v[96:99], v[196:199], v[222:225], v[96:99]
	v_mfma_f32_16x16x32_bf16 v[96:99], v[200:203], v[226:229], v[96:99]
	v_mfma_f32_16x16x32_bf16 v[84:87], v[188:191], v[230:233], v[84:87]
	v_mfma_f32_16x16x32_bf16 v[84:87], v[192:195], v[234:237], v[84:87]
	v_mfma_f32_16x16x32_bf16 v[80:83], v[196:199], v[230:233], v[80:83]
	v_mfma_f32_16x16x32_bf16 v[80:83], v[200:203], v[234:237], v[80:83]
	v_mfma_f32_16x16x32_bf16 v[68:71], v[188:191], v[238:241], v[68:71]
	v_mfma_f32_16x16x32_bf16 v[68:71], v[192:195], v[242:245], v[68:71]
	v_mfma_f32_16x16x32_bf16 v[64:67], v[196:199], v[238:241], v[64:67]
	v_mfma_f32_16x16x32_bf16 v[64:67], v[200:203], v[242:245], v[64:67]
	s_setprio 0
	s_barrier
; #define PG8_STAGE(bufoff, gbase, voff) do { _Pragma("unroll") for (int _i = 0; _i < 2; ++_i) \
;         __builtin_amdgcn_global_load_lds((const unsigned*)((const char*)(gbase) + (voff)[_i]), (PG8_LAS unsigned*)(lds + (bufoff) + ldsw + _i * 8192), 16, 0, 0); } while (0)
; #define PG8_WAIT_V(n) asm volatile("s_waitcnt vmcnt(" #n ")" ::: "memory")
; #define PG8_WAIT_L(n) asm volatile("s_waitcnt lgkmcnt(" #n ")" ::: "memory")
; #define PG8_BAR __builtin_amdgcn_s_barrier()
; #define PG8_SCHED __builtin_amdgcn_sched_barrier(0)
;     ...
;             PG8_LDB(B0, 1, 0); PG8_LDB(B1, 1, 1); PG8_SCHED; PG8_LDA(At, 1, 0); PG8_STAGE(PG8_SA(0, 1), a2 + hstep, voffA);
;             PG8_WAIT_V(8); PG8_WAIT_L(0); PG8_BAR; PG8_MMA(0, 0, At, B0); PG8_MMA(0, 1, At, B1); PG8_BAR; PG8_SCHED;
;             PG8_LDA(At, 1, 1); PG8_STAGE(PG8_SB(1, 0), b3, voffB); PG8_STAGE(PG8_SB(1, 1), b3 + hstep, voffB); PG8_STAGE(PG8_SA(1, 0), a3, voffA);
;             PG8_WAIT_V(8); PG8_WAIT_L(0); PG8_BAR; PG8_MMA(1, 0, At, B0); PG8_MMA(1, 1, At, B1); PG8_BAR; PG8_SCHED;
	s_add_i32 s33, s33, s82
	v_lshl_add_u64 v[146:147], v[146:147], 0, s[50:51]
	s_mov_b32 m0, s33
	ds_read_b128 v[214:217], v159 offset:49152
	ds_read_b128 v[218:221], v159 offset:50176
	ds_read_b128 v[222:225], v159 offset:51200
	ds_read_b128 v[226:229], v159 offset:52224
	ds_read_b128 v[230:233], v159 offset:53248
	ds_read_b128 v[234:237], v159 offset:54272
	ds_read_b128 v[238:241], v159 offset:55296
	ds_read_b128 v[242:245], v159 offset:56320
	global_load_lds_dwordx4 v[146:147], off
	s_add_i32 m0, s33, 0x2000
	s_add_u32 s72, s72, 0x80080
	v_lshl_add_u64 v[146:147], v[246:247], 0, s[50:51]
	s_addc_u32 s73, s73, 0
	s_add_i32 s33, s94, s82
	global_load_lds_dwordx4 v[146:147], off
	v_lshl_add_u64 v[146:147], s[72:73], 0, v[150:151]
	s_mov_b32 m0, s33
	s_nop 0
	global_load_lds_dwordx4 v[146:147], off
	v_lshl_add_u64 v[146:147], s[72:73], 0, v[154:155]
	s_add_i32 m0, s33, 0x2000
	s_nop 0
	global_load_lds_dwordx4 v[146:147], off
	v_lshl_add_u64 v[146:147], v[248:249], 0, s[50:51]
	s_mov_b32 m0, s86
	s_nop 0
	global_load_lds_dwordx4 v[146:147], off
	v_lshl_add_u64 v[146:147], v[250:251], 0, s[50:51]
	s_mov_b32 m0, s87
	s_nop 0
	global_load_lds_dwordx4 v[146:147], off
	s_waitcnt vmcnt(8)
	s_waitcnt lgkmcnt(0)
	s_barrier
	s_setprio 1
	s_waitcnt lgkmcnt(0)
	v_mfma_f32_16x16x32_bf16 v[60:63], v[130:133], v[214:217], v[60:63]
	v_mfma_f32_16x16x32_bf16 v[60:63], v[134:137], v[218:221], v[60:63]
	v_mfma_f32_16x16x32_bf16 v[56:59], v[138:141], v[214:217], v[56:59]
	v_mfma_f32_16x16x32_bf16 v[56:59], v[142:145], v[218:221], v[56:59]
	v_mfma_f32_16x16x32_bf16 v[44:47], v[130:133], v[222:225], v[44:47]
	v_mfma_f32_16x16x32_bf16 v[44:47], v[134:137], v[226:229], v[44:47]
	v_mfma_f32_16x16x32_bf16 v[40:43], v[138:141], v[222:225], v[40:43]
	v_mfma_f32_16x16x32_bf16 v[40:43], v[142:145], v[226:229], v[40:43]
	v_mfma_f32_16x16x32_bf16 v[28:31], v[130:133], v[230:233], v[28:31]
	v_mfma_f32_16x16x32_bf16 v[28:31], v[134:137], v[234:237], v[28:31]
	v_mfma_f32_16x16x32_bf16 v[24:27], v[138:141], v[230:233], v[24:27]
	v_mfma_f32_16x16x32_bf16 v[24:27], v[142:145], v[234:237], v[24:27]
	v_mfma_f32_16x16x32_bf16 v[12:15], v[130:133], v[238:241], v[12:15]
	v_mfma_f32_16x16x32_bf16 v[12:15], v[134:137], v[242:245], v[12:15]
	v_mfma_f32_16x16x32_bf16 v[8:11], v[138:141], v[238:241], v[8:11]
	v_mfma_f32_16x16x32_bf16 v[8:11], v[142:145], v[242:245], v[8:11]
	s_setprio 0
	s_setprio 1
	v_mfma_f32_16x16x32_bf16 v[52:55], v[188:191], v[214:217], v[52:55]
	v_mfma_f32_16x16x32_bf16 v[52:55], v[192:195], v[218:221], v[52:55]
	v_mfma_f32_16x16x32_bf16 v[48:51], v[196:199], v[214:217], v[48:51]
	v_mfma_f32_16x16x32_bf16 v[48:51], v[200:203], v[218:221], v[48:51]
	v_mfma_f32_16x16x32_bf16 v[36:39], v[188:191], v[222:225], v[36:39]
	v_mfma_f32_16x16x32_bf16 v[36:39], v[192:195], v[226:229], v[36:39]
	v_mfma_f32_16x16x32_bf16 v[32:35], v[196:199], v[222:225], v[32:35]
	v_mfma_f32_16x16x32_bf16 v[32:35], v[200:203], v[226:229], v[32:35]
	v_mfma_f32_16x16x32_bf16 v[20:23], v[188:191], v[230:233], v[20:23]
	v_mfma_f32_16x16x32_bf16 v[20:23], v[192:195], v[234:237], v[20:23]
	v_mfma_f32_16x16x32_bf16 v[16:19], v[196:199], v[230:233], v[16:19]
	v_mfma_f32_16x16x32_bf16 v[16:19], v[200:203], v[234:237], v[16:19]
	v_mfma_f32_16x16x32_bf16 v[4:7], v[188:191], v[238:241], v[4:7]
	v_mfma_f32_16x16x32_bf16 v[4:7], v[192:195], v[242:245], v[4:7]
	v_mfma_f32_16x16x32_bf16 v[0:3], v[196:199], v[238:241], v[0:3]
	v_mfma_f32_16x16x32_bf16 v[0:3], v[200:203], v[242:245], v[0:3]
	s_setprio 0
	s_barrier
	s_add_i32 s63, s63, 2
	s_add_u32 s70, s70, 0x100
	s_addc_u32 s71, s71, 0
	s_add_u32 s10, s10, 0x100
	s_addc_u32 s61, s61, 0
	s_cmp_gt_u32 s63, 29
	s_cbranch_scc1 .LBB0_435

; #define PG8_STAGE(bufoff, gbase, voff) do { _Pragma("unroll") for (int _i = 0; _i < 2; ++_i) \
;         __builtin_amdgcn_global_load_lds((const unsigned*)((const char*)(gbase) + (voff)[_i]), (PG8_LAS unsigned*)(lds + (bufoff) + ldsw + _i * 8192), 16, 0, 0); } while (0)
; #define PG8_WAIT_V(n) asm volatile("s_waitcnt vmcnt(" #n ")" ::: "memory")
; #define PG8_WAIT_L(n) asm volatile("s_waitcnt lgkmcnt(" #n ")" ::: "memory")
; #define PG8_BAR __builtin_amdgcn_s_barrier()
; #define PG8_SCHED __builtin_amdgcn_sched_barrier(0)
;     ...
;             PG8_LDB(B0, 0, 0); PG8_LDB(B1, 0, 1); PG8_SCHED; PG8_LDA(At, 0, 0); PG8_STAGE(PG8_SA(1, 1), a1 + hstep, voffA);
;             PG8_WAIT_V(8); PG8_WAIT_L(0); PG8_BAR; PG8_MMA(0, 0, At, B0); PG8_MMA(0, 1, At, B1); PG8_BAR; PG8_SCHED;
;             PG8_LDA(At, 0, 1); PG8_STAGE(PG8_SB(0, 0), b2, voffB); PG8_STAGE(PG8_SB(0, 1), b2 + hstep, voffB); PG8_STAGE(PG8_SA(0, 0), a2, voffA);
;             PG8_WAIT_V(8); PG8_WAIT_L(0); PG8_BAR; PG8_MMA(1, 0, At, B0); PG8_MMA(1, 1, At, B1); PG8_BAR; PG8_SCHED;
;             PG8_LDB(B0, 1, 0); PG8_LDB(B1, 1, 1); PG8_SCHED; PG8_LDA(At, 1, 0); PG8_STAGE(PG8_SA(0, 1), a2 + hstep, voffA);
;             PG8_WAIT_V(8); PG8_WAIT_L(0); PG8_BAR; PG8_MMA(0, 0, At, B0); PG8_MMA(0, 1, At, B1); PG8_BAR; PG8_SCHED;
.LBB0_666:
	v_add_u32_e32 v1, s70, v175
	s_add_u32 s33, s52, s54
	ds_read_b128 v[140:143], v1
	ds_read_b128 v[144:147], v1 offset:1024
	ds_read_b128 v[148:151], v1 offset:2048
	ds_read_b128 v[152:155], v1 offset:3072
	v_add_u32_e32 v1, s71, v175
	s_addc_u32 s58, s53, s55
	ds_read_b128 v[190:193], v1
	ds_read_b128 v[194:197], v1 offset:1024
	ds_read_b128 v[198:201], v1 offset:2048
	ds_read_b128 v[202:205], v1 offset:3072
	s_add_u32 s33, s33, 0x100
	s_addc_u32 s76, s58, 0
	s_and_b64 s[58:59], s[56:57], exec
	s_cselect_b32 s59, s34, s76
	s_cselect_b32 s58, s35, s33
	s_add_u32 s33, s73, s54
	s_addc_u32 s76, s74, s55
	s_and_b64 s[56:57], s[56:57], exec
	s_cselect_b32 s57, s45, s76
	s_cselect_b32 s56, s47, s33
	v_lshl_add_u64 v[2:3], v[136:137], 0, s[54:55]
	s_add_i32 m0, s63, 0xc000
	ds_read_b128 v[206:209], v179
	ds_read_b128 v[214:217], v179 offset:1024
	ds_read_b128 v[218:221], v179 offset:2048
	ds_read_b128 v[222:225], v179 offset:3072
	ds_read_b128 v[226:229], v179 offset:4096
	ds_read_b128 v[230:233], v179 offset:5120
	ds_read_b128 v[234:237], v179 offset:6144
	ds_read_b128 v[238:241], v179 offset:7168
	global_load_lds_dwordx4 v[2:3], off
	v_lshl_add_u64 v[2:3], v[138:139], 0, s[54:55]
	s_add_i32 m0, s63, 0xe000
	s_nop 0
	global_load_lds_dwordx4 v[2:3], off
	s_waitcnt vmcnt(8)
	s_waitcnt lgkmcnt(0)
	s_barrier
	s_setprio 1
	s_waitcnt lgkmcnt(0)
	v_mfma_f32_16x16x32_bf16 v[128:131], v[140:143], v[206:209], v[128:131]
	v_mfma_f32_16x16x32_bf16 v[128:131], v[144:147], v[214:217], v[128:131]
	v_mfma_f32_16x16x32_bf16 v[124:127], v[148:151], v[206:209], v[124:127]
	v_mfma_f32_16x16x32_bf16 v[124:127], v[152:155], v[214:217], v[124:127]
	v_mfma_f32_16x16x32_bf16 v[112:115], v[140:143], v[218:221], v[112:115]
	v_mfma_f32_16x16x32_bf16 v[112:115], v[144:147], v[222:225], v[112:115]
	v_mfma_f32_16x16x32_bf16 v[108:111], v[148:151], v[218:221], v[108:111]
	v_mfma_f32_16x16x32_bf16 v[108:111], v[152:155], v[222:225], v[108:111]
	v_mfma_f32_16x16x32_bf16 v[96:99], v[140:143], v[226:229], v[96:99]
	v_mfma_f32_16x16x32_bf16 v[96:99], v[144:147], v[230:233], v[96:99]
	v_mfma_f32_16x16x32_bf16 v[92:95], v[148:151], v[226:229], v[92:95]
	v_mfma_f32_16x16x32_bf16 v[92:95], v[152:155], v[230:233], v[92:95]
	v_mfma_f32_16x16x32_bf16 v[80:83], v[140:143], v[234:237], v[80:83]
	v_mfma_f32_16x16x32_bf16 v[80:83], v[144:147], v[238:241], v[80:83]
	v_mfma_f32_16x16x32_bf16 v[76:79], v[148:151], v[234:237], v[76:79]
	v_mfma_f32_16x16x32_bf16 v[76:79], v[152:155], v[238:241], v[76:79]
	s_setprio 0
	s_setprio 1
	v_mfma_f32_16x16x32_bf16 v[120:123], v[190:193], v[206:209], v[120:123]
	v_mfma_f32_16x16x32_bf16 v[120:123], v[194:197], v[214:217], v[120:123]
	v_mfma_f32_16x16x32_bf16 v[116:119], v[198:201], v[206:209], v[116:119]
	v_mfma_f32_16x16x32_bf16 v[116:119], v[202:205], v[214:217], v[116:119]
	v_mfma_f32_16x16x32_bf16 v[104:107], v[190:193], v[218:221], v[104:107]
	v_mfma_f32_16x16x32_bf16 v[104:107], v[194:197], v[222:225], v[104:107]
	v_mfma_f32_16x16x32_bf16 v[100:103], v[198:201], v[218:221], v[100:103]
	v_mfma_f32_16x16x32_bf16 v[100:103], v[202:205], v[222:225], v[100:103]
	v_mfma_f32_16x16x32_bf16 v[88:91], v[190:193], v[226:229], v[88:91]
	v_mfma_f32_16x16x32_bf16 v[88:91], v[194:197], v[230:233], v[88:91]
	v_mfma_f32_16x16x32_bf16 v[84:87], v[198:201], v[226:229], v[84:87]
	v_mfma_f32_16x16x32_bf16 v[84:87], v[202:205], v[230:233], v[84:87]
	v_mfma_f32_16x16x32_bf16 v[72:75], v[190:193], v[234:237], v[72:75]
	v_mfma_f32_16x16x32_bf16 v[72:75], v[194:197], v[238:241], v[72:75]
	v_mfma_f32_16x16x32_bf16 v[68:71], v[198:201], v[234:237], v[68:71]
	v_mfma_f32_16x16x32_bf16 v[68:71], v[202:205], v[238:241], v[68:71]
	s_setprio 0
	s_barrier
	s_add_i32 s33, s70, s62
	v_lshl_add_u64 v[210:211], s[56:57], 0, v[158:159]
	s_mov_b32 m0, s33
	ds_read_b128 v[206:209], v179 offset:16384
	ds_read_b128 v[214:217], v179 offset:17408
	ds_read_b128 v[218:221], v179 offset:18432
	ds_read_b128 v[222:225], v179 offset:19456
	ds_read_b128 v[226:229], v179 offset:20480
	ds_read_b128 v[230:233], v179 offset:21504
	ds_read_b128 v[234:237], v179 offset:22528
	ds_read_b128 v[238:241], v179 offset:23552
	global_load_lds_dwordx4 v[210:211], off
	s_add_i32 m0, s33, 0x2000
	s_add_u32 s76, s56, 0x80000
	v_lshl_add_u64 v[242:243], s[56:57], 0, v[162:163]
	s_addc_u32 s77, s57, 0
	s_add_i32 s33, s71, s62
	global_load_lds_dwordx4 v[242:243], off
	v_lshl_add_u64 v[2:3], s[76:77], 0, v[158:159]
	s_mov_b32 m0, s33
	v_lshl_add_u64 v[244:245], s[58:59], 0, v[156:157]
	global_load_lds_dwordx4 v[2:3], off
	v_lshl_add_u64 v[2:3], s[76:77], 0, v[162:163]
	s_add_i32 m0, s33, 0x2000
	v_lshl_add_u64 v[246:247], s[58:59], 0, v[160:161]
	global_load_lds_dwordx4 v[2:3], off
	s_mov_b32 m0, s63
	s_nop 0
	global_load_lds_dwordx4 v[244:245], off
	s_mov_b32 m0, s64
	s_nop 0
	global_load_lds_dwordx4 v[246:247], off
	s_waitcnt vmcnt(8)
	s_waitcnt lgkmcnt(0)
	s_barrier
; #define PG8_STAGE(bufoff, gbase, voff) do { _Pragma("unroll") for (int _i = 0; _i < 2; ++_i) \
;         __builtin_amdgcn_global_load_lds((const unsigned*)((const char*)(gbase) + (voff)[_i]), (PG8_LAS unsigned*)(lds + (bufoff) + ldsw + _i * 8192), 16, 0, 0); } while (0)
; #define PG8_WAIT_V(n) asm volatile("s_waitcnt vmcnt(" #n ")" ::: "memory")
; #define PG8_WAIT_L(n) asm volatile("s_waitcnt lgkmcnt(" #n ")" ::: "memory")
; #define PG8_BAR __builtin_amdgcn_s_barrier()
; #define PG8_SCHED __builtin_amdgcn_sched_barrier(0)
;     ...
;             PG8_LDA(At, 0, 1); PG8_STAGE(PG8_SB(0, 0), b2, voffB); PG8_STAGE(PG8_SB(0, 1), b2 + hstep, voffB); PG8_STAGE(PG8_SA(0, 0), a2, voffA);
;             PG8_WAIT_V(8); PG8_WAIT_L(0); PG8_BAR; PG8_MMA(1, 0, At, B0); PG8_MMA(1, 1, At, B1); PG8_BAR; PG8_SCHED;
;             PG8_LDB(B0, 1, 0); PG8_LDB(B1, 1, 1); PG8_SCHED; PG8_LDA(At, 1, 0); PG8_STAGE(PG8_SA(0, 1), a2 + hstep, voffA);
;             PG8_WAIT_V(8); PG8_WAIT_L(0); PG8_BAR; PG8_MMA(0, 0, At, B0); PG8_MMA(0, 1, At, B1); PG8_BAR; PG8_SCHED;
;             PG8_LDA(At, 1, 1); PG8_STAGE(PG8_SB(1, 0), b3, voffB); PG8_STAGE(PG8_SB(1, 1), b3 + hstep, voffB); PG8_STAGE(PG8_SA(1, 0), a3, voffA);
	s_setprio 1
	s_waitcnt lgkmcnt(0)
	v_mfma_f32_16x16x32_bf16 v[64:67], v[140:143], v[206:209], v[64:67]
	v_mfma_f32_16x16x32_bf16 v[64:67], v[144:147], v[214:217], v[64:67]
	v_mfma_f32_16x16x32_bf16 v[60:63], v[148:151], v[206:209], v[60:63]
	v_mfma_f32_16x16x32_bf16 v[60:63], v[152:155], v[214:217], v[60:63]
	v_mfma_f32_16x16x32_bf16 v[48:51], v[140:143], v[218:221], v[48:51]
	v_mfma_f32_16x16x32_bf16 v[48:51], v[144:147], v[222:225], v[48:51]
	v_mfma_f32_16x16x32_bf16 v[44:47], v[148:151], v[218:221], v[44:47]
	v_mfma_f32_16x16x32_bf16 v[44:47], v[152:155], v[222:225], v[44:47]
	v_mfma_f32_16x16x32_bf16 v[32:35], v[140:143], v[226:229], v[32:35]
	v_mfma_f32_16x16x32_bf16 v[32:35], v[144:147], v[230:233], v[32:35]
	v_mfma_f32_16x16x32_bf16 v[28:31], v[148:151], v[226:229], v[28:31]
	v_mfma_f32_16x16x32_bf16 v[28:31], v[152:155], v[230:233], v[28:31]
	v_mfma_f32_16x16x32_bf16 v[16:19], v[140:143], v[234:237], v[16:19]
	v_mfma_f32_16x16x32_bf16 v[16:19], v[144:147], v[238:241], v[16:19]
	v_mfma_f32_16x16x32_bf16 v[12:15], v[148:151], v[234:237], v[12:15]
	v_mfma_f32_16x16x32_bf16 v[12:15], v[152:155], v[238:241], v[12:15]
	s_setprio 0
	s_setprio 1
	v_mfma_f32_16x16x32_bf16 v[56:59], v[190:193], v[206:209], v[56:59]
	v_mfma_f32_16x16x32_bf16 v[56:59], v[194:197], v[214:217], v[56:59]
	v_mfma_f32_16x16x32_bf16 v[52:55], v[198:201], v[206:209], v[52:55]
	v_mfma_f32_16x16x32_bf16 v[52:55], v[202:205], v[214:217], v[52:55]
	v_mfma_f32_16x16x32_bf16 v[40:43], v[190:193], v[218:221], v[40:43]
	v_mfma_f32_16x16x32_bf16 v[40:43], v[194:197], v[222:225], v[40:43]
	v_mfma_f32_16x16x32_bf16 v[36:39], v[198:201], v[218:221], v[36:39]
	v_mfma_f32_16x16x32_bf16 v[36:39], v[202:205], v[222:225], v[36:39]
	v_mfma_f32_16x16x32_bf16 v[24:27], v[190:193], v[226:229], v[24:27]
	v_mfma_f32_16x16x32_bf16 v[24:27], v[194:197], v[230:233], v[24:27]
	v_mfma_f32_16x16x32_bf16 v[20:23], v[198:201], v[226:229], v[20:23]
	v_mfma_f32_16x16x32_bf16 v[20:23], v[202:205], v[230:233], v[20:23]
	v_mfma_f32_16x16x32_bf16 v[8:11], v[190:193], v[234:237], v[8:11]
	v_mfma_f32_16x16x32_bf16 v[8:11], v[194:197], v[238:241], v[8:11]
	v_mfma_f32_16x16x32_bf16 v[2:5], v[198:201], v[234:237], v[4:7]
	v_mfma_f32_16x16x32_bf16 v[2:5], v[202:205], v[238:241], v[2:5]
	s_setprio 0
	s_barrier
	s_add_i32 s33, 0, 0x18000
	v_add_u32_e32 v1, s33, v175
	s_add_i32 s76, 0, 0x1c000
	ds_read_b128 v[140:143], v1
	ds_read_b128 v[144:147], v1 offset:1024
	ds_read_b128 v[148:151], v1 offset:2048
	ds_read_b128 v[152:155], v1 offset:3072
	v_add_u32_e32 v1, s76, v175
	ds_read_b128 v[190:193], v1
	ds_read_b128 v[194:197], v1 offset:1024
	ds_read_b128 v[198:201], v1 offset:2048
	ds_read_b128 v[202:205], v1 offset:3072
	s_add_u32 s58, s58, 0x80000
	s_addc_u32 s59, s59, 0
	s_mov_b32 m0, s65
	v_lshl_add_u64 v[6:7], s[58:59], 0, v[156:157]
	ds_read_b128 v[206:209], v179 offset:32768
	ds_read_b128 v[214:217], v179 offset:33792
	ds_read_b128 v[218:221], v179 offset:34816
	ds_read_b128 v[222:225], v179 offset:35840
	ds_read_b128 v[226:229], v179 offset:36864
	ds_read_b128 v[230:233], v179 offset:37888
	ds_read_b128 v[234:237], v179 offset:38912
	ds_read_b128 v[238:241], v179 offset:39936
	global_load_lds_dwordx4 v[6:7], off
	v_lshl_add_u64 v[6:7], s[58:59], 0, v[160:161]
	s_mov_b32 m0, s66
	s_nop 0
	global_load_lds_dwordx4 v[6:7], off
	s_waitcnt vmcnt(8)
	s_waitcnt lgkmcnt(0)
	s_barrier
	s_setprio 1
	s_waitcnt lgkmcnt(0)
	v_mfma_f32_16x16x32_bf16 v[128:131], v[140:143], v[206:209], v[128:131]
	v_mfma_f32_16x16x32_bf16 v[128:131], v[144:147], v[214:217], v[128:131]
	v_mfma_f32_16x16x32_bf16 v[124:127], v[148:151], v[206:209], v[124:127]
	v_mfma_f32_16x16x32_bf16 v[124:127], v[152:155], v[214:217], v[124:127]
	v_mfma_f32_16x16x32_bf16 v[112:115], v[140:143], v[218:221], v[112:115]
	v_mfma_f32_16x16x32_bf16 v[112:115], v[144:147], v[222:225], v[112:115]
	v_mfma_f32_16x16x32_bf16 v[108:111], v[148:151], v[218:221], v[108:111]
	v_mfma_f32_16x16x32_bf16 v[108:111], v[152:155], v[222:225], v[108:111]
	v_mfma_f32_16x16x32_bf16 v[96:99], v[140:143], v[226:229], v[96:99]
	v_mfma_f32_16x16x32_bf16 v[96:99], v[144:147], v[230:233], v[96:99]
	v_mfma_f32_16x16x32_bf16 v[92:95], v[148:151], v[226:229], v[92:95]
	v_mfma_f32_16x16x32_bf16 v[92:95], v[152:155], v[230:233], v[92:95]
	v_mfma_f32_16x16x32_bf16 v[80:83], v[140:143], v[234:237], v[80:83]
	v_mfma_f32_16x16x32_bf16 v[80:83], v[144:147], v[238:241], v[80:83]
	v_mfma_f32_16x16x32_bf16 v[76:79], v[148:151], v[234:237], v[76:79]
	v_mfma_f32_16x16x32_bf16 v[76:79], v[152:155], v[238:241], v[76:79]
	s_setprio 0
	s_setprio 1
	v_mfma_f32_16x16x32_bf16 v[120:123], v[190:193], v[206:209], v[120:123]
	v_mfma_f32_16x16x32_bf16 v[120:123], v[194:197], v[214:217], v[120:123]
	v_mfma_f32_16x16x32_bf16 v[116:119], v[198:201], v[206:209], v[116:119]
	v_mfma_f32_16x16x32_bf16 v[116:119], v[202:205], v[214:217], v[116:119]
	v_mfma_f32_16x16x32_bf16 v[104:107], v[190:193], v[218:221], v[104:107]
	v_mfma_f32_16x16x32_bf16 v[104:107], v[194:197], v[222:225], v[104:107]
	v_mfma_f32_16x16x32_bf16 v[100:103], v[198:201], v[218:221], v[100:103]
	v_mfma_f32_16x16x32_bf16 v[100:103], v[202:205], v[222:225], v[100:103]
	v_mfma_f32_16x16x32_bf16 v[88:91], v[190:193], v[226:229], v[88:91]
	v_mfma_f32_16x16x32_bf16 v[88:91], v[194:197], v[230:233], v[88:91]
	v_mfma_f32_16x16x32_bf16 v[84:87], v[198:201], v[226:229], v[84:87]
	v_mfma_f32_16x16x32_bf16 v[84:87], v[202:205], v[230:233], v[84:87]
	v_mfma_f32_16x16x32_bf16 v[72:75], v[190:193], v[234:237], v[72:75]
	v_mfma_f32_16x16x32_bf16 v[72:75], v[194:197], v[238:241], v[72:75]
	v_mfma_f32_16x16x32_bf16 v[68:71], v[198:201], v[234:237], v[68:71]
	v_mfma_f32_16x16x32_bf16 v[68:71], v[202:205], v[238:241], v[68:71]
	s_setprio 0
	s_barrier
; #define PG8_STAGE(bufoff, gbase, voff) do { _Pragma("unroll") for (int _i = 0; _i < 2; ++_i) \
;         __builtin_amdgcn_global_load_lds((const unsigned*)((const char*)(gbase) + (voff)[_i]), (PG8_LAS unsigned*)(lds + (bufoff) + ldsw + _i * 8192), 16, 0, 0); } while (0)
; #define PG8_WAIT_V(n) asm volatile("s_waitcnt vmcnt(" #n ")" ::: "memory")
; #define PG8_WAIT_L(n) asm volatile("s_waitcnt lgkmcnt(" #n ")" ::: "memory")
; #define PG8_BAR __builtin_amdgcn_s_barrier()
; #define PG8_SCHED __builtin_amdgcn_sched_barrier(0)
;     ...
;             PG8_LDB(B0, 1, 0); PG8_LDB(B1, 1, 1); PG8_SCHED; PG8_LDA(At, 1, 0); PG8_STAGE(PG8_SA(0, 1), a2 + hstep, voffA);
;             PG8_WAIT_V(8); PG8_WAIT_L(0); PG8_BAR; PG8_MMA(0, 0, At, B0); PG8_MMA(0, 1, At, B1); PG8_BAR; PG8_SCHED;
;             PG8_LDA(At, 1, 1); PG8_STAGE(PG8_SB(1, 0), b3, voffB); PG8_STAGE(PG8_SB(1, 1), b3 + hstep, voffB); PG8_STAGE(PG8_SA(1, 0), a3, voffA);
;             PG8_WAIT_V(8); PG8_WAIT_L(0); PG8_BAR; PG8_MMA(1, 0, At, B0); PG8_MMA(1, 1, At, B1); PG8_BAR; PG8_SCHED;
	s_add_i32 s33, s33, s62
	v_lshl_add_u64 v[6:7], v[210:211], 0, s[40:41]
	s_mov_b32 m0, s33
	ds_read_b128 v[206:209], v179 offset:49152
	ds_read_b128 v[214:217], v179 offset:50176
	ds_read_b128 v[218:221], v179 offset:51200
	ds_read_b128 v[222:225], v179 offset:52224
	ds_read_b128 v[226:229], v179 offset:53248
	ds_read_b128 v[230:233], v179 offset:54272
	ds_read_b128 v[234:237], v179 offset:55296
	ds_read_b128 v[238:241], v179 offset:56320
	global_load_lds_dwordx4 v[6:7], off
	s_add_i32 m0, s33, 0x2000
	s_add_u32 s56, s56, 0x80080
	v_lshl_add_u64 v[6:7], v[242:243], 0, s[40:41]
	s_addc_u32 s57, s57, 0
	s_add_i32 s33, s76, s62
	global_load_lds_dwordx4 v[6:7], off
	v_lshl_add_u64 v[6:7], s[56:57], 0, v[158:159]
	s_mov_b32 m0, s33
	s_nop 0
	global_load_lds_dwordx4 v[6:7], off
	v_lshl_add_u64 v[6:7], s[56:57], 0, v[162:163]
	s_add_i32 m0, s33, 0x2000
	s_nop 0
	global_load_lds_dwordx4 v[6:7], off
	v_lshl_add_u64 v[6:7], v[244:245], 0, s[40:41]
	s_mov_b32 m0, s68
	s_nop 0
	global_load_lds_dwordx4 v[6:7], off
	v_lshl_add_u64 v[6:7], v[246:247], 0, s[40:41]
	s_mov_b32 m0, s69
	s_nop 0
	global_load_lds_dwordx4 v[6:7], off
	s_waitcnt vmcnt(8)
	s_waitcnt lgkmcnt(0)
	s_barrier
	s_setprio 1
	s_waitcnt lgkmcnt(0)
	v_mfma_f32_16x16x32_bf16 v[64:67], v[140:143], v[206:209], v[64:67]
	v_mfma_f32_16x16x32_bf16 v[64:67], v[144:147], v[214:217], v[64:67]
	v_mfma_f32_16x16x32_bf16 v[60:63], v[148:151], v[206:209], v[60:63]
	v_mfma_f32_16x16x32_bf16 v[60:63], v[152:155], v[214:217], v[60:63]
	v_mfma_f32_16x16x32_bf16 v[48:51], v[140:143], v[218:221], v[48:51]
	v_mfma_f32_16x16x32_bf16 v[48:51], v[144:147], v[222:225], v[48:51]
	v_mfma_f32_16x16x32_bf16 v[44:47], v[148:151], v[218:221], v[44:47]
	v_mfma_f32_16x16x32_bf16 v[44:47], v[152:155], v[222:225], v[44:47]
	v_mfma_f32_16x16x32_bf16 v[32:35], v[140:143], v[226:229], v[32:35]
	v_mfma_f32_16x16x32_bf16 v[32:35], v[144:147], v[230:233], v[32:35]
	v_mfma_f32_16x16x32_bf16 v[28:31], v[148:151], v[226:229], v[28:31]
	v_mfma_f32_16x16x32_bf16 v[28:31], v[152:155], v[230:233], v[28:31]
	v_mfma_f32_16x16x32_bf16 v[16:19], v[140:143], v[234:237], v[16:19]
	v_mfma_f32_16x16x32_bf16 v[16:19], v[144:147], v[238:241], v[16:19]
	v_mfma_f32_16x16x32_bf16 v[12:15], v[148:151], v[234:237], v[12:15]
	v_mfma_f32_16x16x32_bf16 v[12:15], v[152:155], v[238:241], v[12:15]
	s_setprio 0
	s_setprio 1
	v_mfma_f32_16x16x32_bf16 v[56:59], v[190:193], v[206:209], v[56:59]
	v_mfma_f32_16x16x32_bf16 v[52:55], v[198:201], v[206:209], v[52:55]
	v_mfma_f32_16x16x32_bf16 v[40:43], v[190:193], v[218:221], v[40:43]
	v_mfma_f32_16x16x32_bf16 v[36:39], v[198:201], v[218:221], v[36:39]
	v_mfma_f32_16x16x32_bf16 v[24:27], v[190:193], v[226:229], v[24:27]
	v_mfma_f32_16x16x32_bf16 v[20:23], v[198:201], v[226:229], v[20:23]
	v_mfma_f32_16x16x32_bf16 v[6:9], v[190:193], v[234:237], v[8:11]
	v_mfma_f32_16x16x32_bf16 v[2:5], v[198:201], v[234:237], v[2:5]
	v_mfma_f32_16x16x32_bf16 v[56:59], v[194:197], v[214:217], v[56:59]
	v_mfma_f32_16x16x32_bf16 v[52:55], v[202:205], v[214:217], v[52:55]
	v_mfma_f32_16x16x32_bf16 v[40:43], v[194:197], v[222:225], v[40:43]
	v_mfma_f32_16x16x32_bf16 v[36:39], v[202:205], v[222:225], v[36:39]
	v_mfma_f32_16x16x32_bf16 v[24:27], v[194:197], v[230:233], v[24:27]
	v_mfma_f32_16x16x32_bf16 v[20:23], v[202:205], v[230:233], v[20:23]
	v_mfma_f32_16x16x32_bf16 v[8:11], v[194:197], v[238:241], v[6:9]
	v_mfma_f32_16x16x32_bf16 v[4:7], v[202:205], v[238:241], v[2:5]
	s_setprio 0
	s_barrier
	s_add_i32 s75, s75, 2
	s_add_u32 s54, s54, 0x100
	s_addc_u32 s55, s55, 0
	s_cmp_gt_u32 s75, 29
	s_cbranch_scc1 .LBB0_671

; #define PG8_STAGE(bufoff, gbase, voff) do { _Pragma("unroll") for (int _i = 0; _i < 2; ++_i) \
;         __builtin_amdgcn_global_load_lds((const unsigned*)((const char*)(gbase) + (voff)[_i]), (PG8_LAS unsigned*)(lds + (bufoff) + ldsw + _i * 8192), 16, 0, 0); } while (0)
; #define PG8_WAIT_V(n) asm volatile("s_waitcnt vmcnt(" #n ")" ::: "memory")
; #define PG8_WAIT_L(n) asm volatile("s_waitcnt lgkmcnt(" #n ")" ::: "memory")
; #define PG8_BAR __builtin_amdgcn_s_barrier()
; #define PG8_SCHED __builtin_amdgcn_sched_barrier(0)
;     ...
;             PG8_LDB(B0, 0, 0); PG8_LDB(B1, 0, 1); PG8_SCHED; PG8_LDA(At, 0, 0); PG8_STAGE(PG8_SA(1, 1), a1 + hstep, voffA);
;             PG8_WAIT_V(8); PG8_WAIT_L(0); PG8_BAR; PG8_MMA(0, 0, At, B0); PG8_MMA(0, 1, At, B1); PG8_BAR; PG8_SCHED;
;             PG8_LDA(At, 0, 1); PG8_STAGE(PG8_SB(0, 0), b2, voffB); PG8_STAGE(PG8_SB(0, 1), b2 + hstep, voffB); PG8_STAGE(PG8_SA(0, 0), a2, voffA);
;             PG8_WAIT_V(8); PG8_WAIT_L(0); PG8_BAR; PG8_MMA(1, 0, At, B0); PG8_MMA(1, 1, At, B1); PG8_BAR; PG8_SCHED;
;             PG8_LDB(B0, 1, 0); PG8_LDB(B1, 1, 1); PG8_SCHED; PG8_LDA(At, 1, 0); PG8_STAGE(PG8_SA(0, 1), a2 + hstep, voffA);
;             PG8_WAIT_V(8); PG8_WAIT_L(0); PG8_BAR; PG8_MMA(0, 0, At, B0); PG8_MMA(0, 1, At, B1); PG8_BAR; PG8_SCHED;
.LBB0_851:
	v_add_u32_e32 v157, s60, v149
	ds_read_b128 v[166:169], v157
	ds_read_b128 v[170:173], v157 offset:1024
	ds_read_b128 v[174:177], v157 offset:2048
	ds_read_b128 v[178:181], v157 offset:3072
	v_add_u32_e32 v157, s61, v149
	ds_read_b128 v[182:185], v157
	ds_read_b128 v[186:189], v157 offset:1024
	ds_read_b128 v[190:193], v157 offset:2048
	ds_read_b128 v[194:197], v157 offset:3072
	s_add_u32 s33, s42, 0xfffc0080
	s_addc_u32 s46, s43, -1
	s_and_b64 s[44:45], s[44:45], exec
	s_cselect_b32 s47, s34, s46
	s_cselect_b32 s46, s35, s33
	s_cselect_b32 s45, s25, s66
	s_cselect_b32 s44, s37, s65
	v_lshl_add_u64 v[210:211], s[42:43], 0, v[138:139]
	s_add_i32 m0, s51, 0xc000
	ds_read_b128 v[198:201], v153
	ds_read_b128 v[202:205], v153 offset:1024
	ds_read_b128 v[206:209], v153 offset:2048
	ds_read_b128 v[214:217], v153 offset:3072
	ds_read_b128 v[218:221], v153 offset:4096
	ds_read_b128 v[222:225], v153 offset:5120
	ds_read_b128 v[226:229], v153 offset:6144
	ds_read_b128 v[230:233], v153 offset:7168
	global_load_lds_dwordx4 v[210:211], off
	v_lshl_add_u64 v[210:211], s[42:43], 0, v[140:141]
	s_add_i32 m0, s51, 0xe000
	s_nop 0
	global_load_lds_dwordx4 v[210:211], off
	s_waitcnt vmcnt(8)
	s_waitcnt lgkmcnt(0)
	s_barrier
	s_setprio 1
	s_waitcnt lgkmcnt(0)
	v_mfma_i32_16x16x64_i8 v[124:127], v[166:169], v[198:201], v[124:127]
	v_mfma_i32_16x16x64_i8 v[124:127], v[170:173], v[202:205], v[124:127]
	v_mfma_i32_16x16x64_i8 v[120:123], v[174:177], v[198:201], v[120:123]
	v_mfma_i32_16x16x64_i8 v[120:123], v[178:181], v[202:205], v[120:123]
	v_mfma_i32_16x16x64_i8 v[108:111], v[166:169], v[206:209], v[108:111]
	v_mfma_i32_16x16x64_i8 v[108:111], v[170:173], v[214:217], v[108:111]
	v_mfma_i32_16x16x64_i8 v[100:103], v[174:177], v[206:209], v[100:103]
	v_mfma_i32_16x16x64_i8 v[100:103], v[178:181], v[214:217], v[100:103]
	v_mfma_i32_16x16x64_i8 v[92:95], v[166:169], v[218:221], v[92:95]
	v_mfma_i32_16x16x64_i8 v[92:95], v[170:173], v[222:225], v[92:95]
	v_mfma_i32_16x16x64_i8 v[84:87], v[174:177], v[218:221], v[84:87]
	v_mfma_i32_16x16x64_i8 v[84:87], v[178:181], v[222:225], v[84:87]
	v_mfma_i32_16x16x64_i8 v[76:79], v[166:169], v[226:229], v[76:79]
	v_mfma_i32_16x16x64_i8 v[76:79], v[170:173], v[230:233], v[76:79]
	v_mfma_i32_16x16x64_i8 v[68:71], v[174:177], v[226:229], v[68:71]
	v_mfma_i32_16x16x64_i8 v[68:71], v[178:181], v[230:233], v[68:71]
	s_setprio 0
	s_setprio 1
	v_mfma_i32_16x16x64_i8 v[116:119], v[182:185], v[198:201], v[116:119]
	v_mfma_i32_16x16x64_i8 v[116:119], v[186:189], v[202:205], v[116:119]
	v_mfma_i32_16x16x64_i8 v[112:115], v[190:193], v[198:201], v[112:115]
	v_mfma_i32_16x16x64_i8 v[112:115], v[194:197], v[202:205], v[112:115]
	v_mfma_i32_16x16x64_i8 v[104:107], v[182:185], v[206:209], v[104:107]
	v_mfma_i32_16x16x64_i8 v[104:107], v[186:189], v[214:217], v[104:107]
	v_mfma_i32_16x16x64_i8 v[96:99], v[190:193], v[206:209], v[96:99]
	v_mfma_i32_16x16x64_i8 v[96:99], v[194:197], v[214:217], v[96:99]
	v_mfma_i32_16x16x64_i8 v[88:91], v[182:185], v[218:221], v[88:91]
	v_mfma_i32_16x16x64_i8 v[88:91], v[186:189], v[222:225], v[88:91]
	v_mfma_i32_16x16x64_i8 v[80:83], v[190:193], v[218:221], v[80:83]
	v_mfma_i32_16x16x64_i8 v[80:83], v[194:197], v[222:225], v[80:83]
	v_mfma_i32_16x16x64_i8 v[72:75], v[182:185], v[226:229], v[72:75]
	v_mfma_i32_16x16x64_i8 v[72:75], v[186:189], v[230:233], v[72:75]
	v_mfma_i32_16x16x64_i8 v[64:67], v[190:193], v[226:229], v[64:67]
	v_mfma_i32_16x16x64_i8 v[64:67], v[194:197], v[230:233], v[64:67]
	s_setprio 0
	s_barrier
	s_add_i32 s33, s60, s48
	v_lshl_add_u64 v[210:211], s[44:45], 0, v[132:133]
	s_mov_b32 m0, s33
	ds_read_b128 v[198:201], v153 offset:16384
	ds_read_b128 v[202:205], v153 offset:17408
	ds_read_b128 v[206:209], v153 offset:18432
	ds_read_b128 v[214:217], v153 offset:19456
	ds_read_b128 v[218:221], v153 offset:20480
	ds_read_b128 v[222:225], v153 offset:21504
	ds_read_b128 v[226:229], v153 offset:22528
	ds_read_b128 v[230:233], v153 offset:23552
	global_load_lds_dwordx4 v[210:211], off
	s_add_i32 m0, s33, 0x2000
	s_add_u32 s68, s44, 0x40000
	v_lshl_add_u64 v[234:235], s[44:45], 0, v[128:129]
	s_addc_u32 s69, s45, 0
	s_add_i32 s33, s61, s48
	global_load_lds_dwordx4 v[234:235], off
	v_lshl_add_u64 v[236:237], s[68:69], 0, v[132:133]
	s_mov_b32 m0, s33
	v_lshl_add_u64 v[238:239], s[46:47], 0, v[130:131]
	global_load_lds_dwordx4 v[236:237], off
	v_lshl_add_u64 v[236:237], s[68:69], 0, v[128:129]
	s_add_i32 m0, s33, 0x2000
	s_nop 0
	global_load_lds_dwordx4 v[236:237], off
	v_lshl_add_u64 v[236:237], s[46:47], 0, v[134:135]
	s_mov_b32 m0, s51
	s_nop 0
	global_load_lds_dwordx4 v[236:237], off
	s_mov_b32 m0, s52
	s_nop 0
	global_load_lds_dwordx4 v[238:239], off
	s_waitcnt vmcnt(8)
	s_waitcnt lgkmcnt(0)
	s_barrier
; #define PG8_STAGE(bufoff, gbase, voff) do { _Pragma("unroll") for (int _i = 0; _i < 2; ++_i) \
;         __builtin_amdgcn_global_load_lds((const unsigned*)((const char*)(gbase) + (voff)[_i]), (PG8_LAS unsigned*)(lds + (bufoff) + ldsw + _i * 8192), 16, 0, 0); } while (0)
; #define PG8_WAIT_V(n) asm volatile("s_waitcnt vmcnt(" #n ")" ::: "memory")
; #define PG8_WAIT_L(n) asm volatile("s_waitcnt lgkmcnt(" #n ")" ::: "memory")
; #define PG8_BAR __builtin_amdgcn_s_barrier()
; #define PG8_SCHED __builtin_amdgcn_sched_barrier(0)
;     ...
;             PG8_LDA(At, 0, 1); PG8_STAGE(PG8_SB(0, 0), b2, voffB); PG8_STAGE(PG8_SB(0, 1), b2 + hstep, voffB); PG8_STAGE(PG8_SA(0, 0), a2, voffA);
;             PG8_WAIT_V(8); PG8_WAIT_L(0); PG8_BAR; PG8_MMA(1, 0, At, B0); PG8_MMA(1, 1, At, B1); PG8_BAR; PG8_SCHED;
;             PG8_LDB(B0, 1, 0); PG8_LDB(B1, 1, 1); PG8_SCHED; PG8_LDA(At, 1, 0); PG8_STAGE(PG8_SA(0, 1), a2 + hstep, voffA);
;             PG8_WAIT_V(8); PG8_WAIT_L(0); PG8_BAR; PG8_MMA(0, 0, At, B0); PG8_MMA(0, 1, At, B1); PG8_BAR; PG8_SCHED;
;             PG8_LDA(At, 1, 1); PG8_STAGE(PG8_SB(1, 0), b3, voffB); PG8_STAGE(PG8_SB(1, 1), b3 + hstep, voffB); PG8_STAGE(PG8_SA(1, 0), a3, voffA);
;             PG8_WAIT_V(8); PG8_WAIT_L(0); PG8_BAR; PG8_MMA(1, 0, At, B0); PG8_MMA(1, 1, At, B1); PG8_BAR; PG8_SCHED;
	s_setprio 1
	s_waitcnt lgkmcnt(0)
	v_mfma_i32_16x16x64_i8 v[60:63], v[166:169], v[198:201], v[60:63]
	v_mfma_i32_16x16x64_i8 v[60:63], v[170:173], v[202:205], v[60:63]
	v_mfma_i32_16x16x64_i8 v[52:55], v[174:177], v[198:201], v[52:55]
	v_mfma_i32_16x16x64_i8 v[52:55], v[178:181], v[202:205], v[52:55]
	v_mfma_i32_16x16x64_i8 v[44:47], v[166:169], v[206:209], v[44:47]
	v_mfma_i32_16x16x64_i8 v[44:47], v[170:173], v[214:217], v[44:47]
	v_mfma_i32_16x16x64_i8 v[36:39], v[174:177], v[206:209], v[36:39]
	v_mfma_i32_16x16x64_i8 v[36:39], v[178:181], v[214:217], v[36:39]
	v_mfma_i32_16x16x64_i8 v[28:31], v[166:169], v[218:221], v[28:31]
	v_mfma_i32_16x16x64_i8 v[28:31], v[170:173], v[222:225], v[28:31]
	v_mfma_i32_16x16x64_i8 v[20:23], v[174:177], v[218:221], v[20:23]
	v_mfma_i32_16x16x64_i8 v[20:23], v[178:181], v[222:225], v[20:23]
	v_mfma_i32_16x16x64_i8 v[12:15], v[166:169], v[226:229], v[12:15]
	v_mfma_i32_16x16x64_i8 v[12:15], v[170:173], v[230:233], v[12:15]
	v_mfma_i32_16x16x64_i8 v[4:7], v[174:177], v[226:229], v[4:7]
	v_mfma_i32_16x16x64_i8 v[4:7], v[178:181], v[230:233], v[4:7]
	s_setprio 0
	s_setprio 1
	v_mfma_i32_16x16x64_i8 v[56:59], v[182:185], v[198:201], v[56:59]
	v_mfma_i32_16x16x64_i8 v[56:59], v[186:189], v[202:205], v[56:59]
	v_mfma_i32_16x16x64_i8 v[48:51], v[190:193], v[198:201], v[48:51]
	v_mfma_i32_16x16x64_i8 v[48:51], v[194:197], v[202:205], v[48:51]
	v_mfma_i32_16x16x64_i8 v[40:43], v[182:185], v[206:209], v[40:43]
	v_mfma_i32_16x16x64_i8 v[40:43], v[186:189], v[214:217], v[40:43]
	v_mfma_i32_16x16x64_i8 v[32:35], v[190:193], v[206:209], v[32:35]
	v_mfma_i32_16x16x64_i8 v[32:35], v[194:197], v[214:217], v[32:35]
	v_mfma_i32_16x16x64_i8 v[24:27], v[182:185], v[218:221], v[24:27]
	v_mfma_i32_16x16x64_i8 v[24:27], v[186:189], v[222:225], v[24:27]
	v_mfma_i32_16x16x64_i8 v[16:19], v[190:193], v[218:221], v[16:19]
	v_mfma_i32_16x16x64_i8 v[16:19], v[194:197], v[222:225], v[16:19]
	v_mfma_i32_16x16x64_i8 v[8:11], v[182:185], v[226:229], v[8:11]
	v_mfma_i32_16x16x64_i8 v[8:11], v[186:189], v[230:233], v[8:11]
	v_mfma_i32_16x16x64_i8 v[0:3], v[190:193], v[226:229], v[0:3]
	v_mfma_i32_16x16x64_i8 v[0:3], v[194:197], v[230:233], v[0:3]
	s_setprio 0
	s_barrier
	s_add_i32 s33, 0, 0x18000
	v_add_u32_e32 v157, s33, v149
	s_add_i32 s68, 0, 0x1c000
	ds_read_b128 v[166:169], v157
	ds_read_b128 v[170:173], v157 offset:1024
	ds_read_b128 v[174:177], v157 offset:2048
	ds_read_b128 v[178:181], v157 offset:3072
	v_add_u32_e32 v157, s68, v149
	ds_read_b128 v[182:185], v157
	ds_read_b128 v[186:189], v157 offset:1024
	ds_read_b128 v[190:193], v157 offset:2048
	ds_read_b128 v[194:197], v157 offset:3072
	s_add_u32 s46, s46, 0x40000
	s_addc_u32 s47, s47, 0
	s_mov_b32 m0, s53
	v_lshl_add_u64 v[240:241], s[46:47], 0, v[134:135]
	ds_read_b128 v[198:201], v153 offset:32768
	ds_read_b128 v[202:205], v153 offset:33792
	ds_read_b128 v[206:209], v153 offset:34816
	ds_read_b128 v[214:217], v153 offset:35840
	ds_read_b128 v[218:221], v153 offset:36864
	ds_read_b128 v[222:225], v153 offset:37888
	ds_read_b128 v[226:229], v153 offset:38912
	ds_read_b128 v[230:233], v153 offset:39936
	global_load_lds_dwordx4 v[240:241], off
	v_lshl_add_u64 v[240:241], s[46:47], 0, v[130:131]
	s_mov_b32 m0, s54
	s_nop 0
	global_load_lds_dwordx4 v[240:241], off
	s_waitcnt vmcnt(8)
	s_waitcnt lgkmcnt(0)
	s_barrier
	s_setprio 1
	s_waitcnt lgkmcnt(0)
	v_mfma_i32_16x16x64_i8 v[124:127], v[166:169], v[198:201], v[124:127]
	v_mfma_i32_16x16x64_i8 v[124:127], v[170:173], v[202:205], v[124:127]
	v_mfma_i32_16x16x64_i8 v[120:123], v[174:177], v[198:201], v[120:123]
	v_mfma_i32_16x16x64_i8 v[120:123], v[178:181], v[202:205], v[120:123]
	v_mfma_i32_16x16x64_i8 v[108:111], v[166:169], v[206:209], v[108:111]
	v_mfma_i32_16x16x64_i8 v[108:111], v[170:173], v[214:217], v[108:111]
	v_mfma_i32_16x16x64_i8 v[100:103], v[174:177], v[206:209], v[100:103]
	v_mfma_i32_16x16x64_i8 v[100:103], v[178:181], v[214:217], v[100:103]
	v_mfma_i32_16x16x64_i8 v[92:95], v[166:169], v[218:221], v[92:95]
	v_mfma_i32_16x16x64_i8 v[92:95], v[170:173], v[222:225], v[92:95]
	v_mfma_i32_16x16x64_i8 v[84:87], v[174:177], v[218:221], v[84:87]
	v_mfma_i32_16x16x64_i8 v[84:87], v[178:181], v[222:225], v[84:87]
	v_mfma_i32_16x16x64_i8 v[76:79], v[166:169], v[226:229], v[76:79]
	v_mfma_i32_16x16x64_i8 v[76:79], v[170:173], v[230:233], v[76:79]
	v_mfma_i32_16x16x64_i8 v[68:71], v[174:177], v[226:229], v[68:71]
	v_mfma_i32_16x16x64_i8 v[68:71], v[178:181], v[230:233], v[68:71]
	s_setprio 0
	s_setprio 1
	v_mfma_i32_16x16x64_i8 v[116:119], v[182:185], v[198:201], v[116:119]
	v_mfma_i32_16x16x64_i8 v[116:119], v[186:189], v[202:205], v[116:119]
	v_mfma_i32_16x16x64_i8 v[112:115], v[190:193], v[198:201], v[112:115]
	v_mfma_i32_16x16x64_i8 v[112:115], v[194:197], v[202:205], v[112:115]
	v_mfma_i32_16x16x64_i8 v[104:107], v[182:185], v[206:209], v[104:107]
	v_mfma_i32_16x16x64_i8 v[104:107], v[186:189], v[214:217], v[104:107]
	v_mfma_i32_16x16x64_i8 v[96:99], v[190:193], v[206:209], v[96:99]
	v_mfma_i32_16x16x64_i8 v[96:99], v[194:197], v[214:217], v[96:99]
	v_mfma_i32_16x16x64_i8 v[88:91], v[182:185], v[218:221], v[88:91]
	v_mfma_i32_16x16x64_i8 v[88:91], v[186:189], v[222:225], v[88:91]
	v_mfma_i32_16x16x64_i8 v[80:83], v[190:193], v[218:221], v[80:83]
	v_mfma_i32_16x16x64_i8 v[80:83], v[194:197], v[222:225], v[80:83]
	v_mfma_i32_16x16x64_i8 v[72:75], v[182:185], v[226:229], v[72:75]
	v_mfma_i32_16x16x64_i8 v[72:75], v[186:189], v[230:233], v[72:75]
	v_mfma_i32_16x16x64_i8 v[64:67], v[190:193], v[226:229], v[64:67]
	v_mfma_i32_16x16x64_i8 v[64:67], v[194:197], v[230:233], v[64:67]
	s_setprio 0
	s_barrier
	s_add_i32 s33, s33, s48
	v_lshl_add_u64 v[210:211], v[210:211], 0, s[10:11]
	s_mov_b32 m0, s33
	ds_read_b128 v[198:201], v153 offset:49152
	ds_read_b128 v[202:205], v153 offset:50176
	ds_read_b128 v[206:209], v153 offset:51200
	ds_read_b128 v[214:217], v153 offset:52224
	ds_read_b128 v[218:221], v153 offset:53248
	ds_read_b128 v[222:225], v153 offset:54272
	ds_read_b128 v[226:229], v153 offset:55296
	ds_read_b128 v[230:233], v153 offset:56320
	global_load_lds_dwordx4 v[210:211], off
	s_add_i32 m0, s33, 0x2000
	s_add_u32 s44, s44, 0x40080
	v_lshl_add_u64 v[210:211], v[234:235], 0, s[10:11]
	s_addc_u32 s45, s45, 0
	s_add_i32 s33, s68, s48
	global_load_lds_dwordx4 v[210:211], off
	v_lshl_add_u64 v[210:211], s[44:45], 0, v[132:133]
	s_mov_b32 m0, s33
	s_nop 0
	global_load_lds_dwordx4 v[210:211], off
	v_lshl_add_u64 v[210:211], s[44:45], 0, v[128:129]
	s_add_i32 m0, s33, 0x2000
	s_nop 0
	global_load_lds_dwordx4 v[210:211], off
	v_lshl_add_u64 v[210:211], v[236:237], 0, s[10:11]
	s_mov_b32 m0, s56
	s_nop 0
	global_load_lds_dwordx4 v[210:211], off
	v_lshl_add_u64 v[210:211], v[238:239], 0, s[10:11]
	s_mov_b32 m0, s57
	s_nop 0
	global_load_lds_dwordx4 v[210:211], off
	s_waitcnt vmcnt(8)
	s_waitcnt lgkmcnt(0)
	s_barrier
	s_cmp_eq_u32 s67, 12
	s_cbranch_scc1 .Lp9_cm_load
; #define PG8_WAIT_V(n) asm volatile("s_waitcnt vmcnt(" #n ")" ::: "memory")
; #define PG8_WAIT_L(n) asm volatile("s_waitcnt lgkmcnt(" #n ")" ::: "memory")
; #define PG8_BAR __builtin_amdgcn_s_barrier()
; #define PG8_SCHED __builtin_amdgcn_sched_barrier(0)
;     ...
;         for (int t = 0; t < nt; t += 2) {
;     ...
;             PG8_WAIT_V(8); PG8_WAIT_L(0); PG8_BAR; PG8_MMA(1, 0, At, B0); PG8_MMA(1, 1, At, B1); PG8_BAR; PG8_SCHED;
.Lp9_cm_back:
	s_setprio 1
	s_waitcnt lgkmcnt(0)
	v_mfma_i32_16x16x64_i8 v[60:63], v[166:169], v[198:201], v[60:63]
	v_mfma_i32_16x16x64_i8 v[60:63], v[170:173], v[202:205], v[60:63]
	v_mfma_i32_16x16x64_i8 v[52:55], v[174:177], v[198:201], v[52:55]
	v_mfma_i32_16x16x64_i8 v[52:55], v[178:181], v[202:205], v[52:55]
	v_mfma_i32_16x16x64_i8 v[44:47], v[166:169], v[206:209], v[44:47]
	v_mfma_i32_16x16x64_i8 v[44:47], v[170:173], v[214:217], v[44:47]
	v_mfma_i32_16x16x64_i8 v[36:39], v[174:177], v[206:209], v[36:39]
	v_mfma_i32_16x16x64_i8 v[36:39], v[178:181], v[214:217], v[36:39]
	v_mfma_i32_16x16x64_i8 v[28:31], v[166:169], v[218:221], v[28:31]
	v_mfma_i32_16x16x64_i8 v[28:31], v[170:173], v[222:225], v[28:31]
	v_mfma_i32_16x16x64_i8 v[20:23], v[174:177], v[218:221], v[20:23]
	v_mfma_i32_16x16x64_i8 v[20:23], v[178:181], v[222:225], v[20:23]
	v_mfma_i32_16x16x64_i8 v[12:15], v[166:169], v[226:229], v[12:15]
	v_mfma_i32_16x16x64_i8 v[12:15], v[170:173], v[230:233], v[12:15]
	v_mfma_i32_16x16x64_i8 v[4:7], v[174:177], v[226:229], v[4:7]
	v_mfma_i32_16x16x64_i8 v[4:7], v[178:181], v[230:233], v[4:7]
	s_setprio 0
	s_setprio 1
	v_mfma_i32_16x16x64_i8 v[56:59], v[182:185], v[198:201], v[56:59]
	v_mfma_i32_16x16x64_i8 v[56:59], v[186:189], v[202:205], v[56:59]
	v_mfma_i32_16x16x64_i8 v[48:51], v[190:193], v[198:201], v[48:51]
	v_mfma_i32_16x16x64_i8 v[48:51], v[194:197], v[202:205], v[48:51]
	v_mfma_i32_16x16x64_i8 v[40:43], v[182:185], v[206:209], v[40:43]
	v_mfma_i32_16x16x64_i8 v[40:43], v[186:189], v[214:217], v[40:43]
	v_mfma_i32_16x16x64_i8 v[32:35], v[190:193], v[206:209], v[32:35]
	v_mfma_i32_16x16x64_i8 v[32:35], v[194:197], v[214:217], v[32:35]
	v_mfma_i32_16x16x64_i8 v[24:27], v[182:185], v[218:221], v[24:27]
	v_mfma_i32_16x16x64_i8 v[24:27], v[186:189], v[222:225], v[24:27]
	v_mfma_i32_16x16x64_i8 v[16:19], v[190:193], v[218:221], v[16:19]
	v_mfma_i32_16x16x64_i8 v[16:19], v[194:197], v[222:225], v[16:19]
	v_mfma_i32_16x16x64_i8 v[8:11], v[182:185], v[226:229], v[8:11]
	v_mfma_i32_16x16x64_i8 v[8:11], v[186:189], v[230:233], v[8:11]
	v_mfma_i32_16x16x64_i8 v[0:3], v[190:193], v[226:229], v[0:3]
	v_mfma_i32_16x16x64_i8 v[0:3], v[194:197], v[230:233], v[0:3]
	s_setprio 0
	s_barrier
	s_add_i32 s67, s67, 2
	s_add_u32 s42, s42, 0x100
	s_addc_u32 s43, s43, 0
	s_add_u32 s65, s65, 0x100
	s_addc_u32 s66, s66, 0
	s_cmp_gt_u32 s67, 13
	s_cbranch_scc1 .LBB0_854
